# GEMM main loops: loop-carried scalar updates and exit test moved in front of the loop-back barrier; 13-round block search
# baseline (speedup 1.0000x reference)
; #define PG8_STAGE(bufoff, gbase, voff) do { _Pragma("unroll") for (int _i = 0; _i < 2; ++_i) \
;         __builtin_amdgcn_global_load_lds((const unsigned*)((const char*)(gbase) + (voff)[_i]), (LAS unsigned*)(lds + (bufoff) + ldsw + _i * 8192), 16, 0, 0); } while (0)
; #define PG8_LDA(dst, b, h) do { _Pragma("unroll") for (int m = 0; m < 4; ++m) _Pragma("unroll") for (int k = 0; k < 2; ++k) dst[m][k] = *(const LAS bf16x8*)(lds + PG8_SA(b, h) + aoff + m * 2048 + k * 1024); } while (0)
; #define PG8_LDB(dst, b, h) do { _Pragma("unroll") for (int n = 0; n < 2; ++n) _Pragma("unroll") for (int k = 0; k < 2; ++k) dst[n][k] = *(const LAS bf16x8*)(lds + PG8_SB(b, h) + boff + n * 2048 + k * 1024); } while (0)
; #define PG8_MMA(ai, bj, At, Bt) do { __builtin_amdgcn_s_setprio(1); _Pragma("unroll") for (int m = 0; m < 4; ++m) _Pragma("unroll") for (int n = 0; n < 2; ++n) _Pragma("unroll") for (int k = 0; k < 2; ++k) \
;         acc[ai][bj][m][n] = __builtin_amdgcn_mfma_f32_16x16x32_bf16(Bt[n][k], At[m][k], acc[ai][bj][m][n], 0, 0, 0); __builtin_amdgcn_s_setprio(0); } while (0)
; #define PG8_WAIT_V(n) asm volatile("s_waitcnt vmcnt(" #n ")" ::: "memory")
; #define PG8_WAIT_L(n) asm volatile("s_waitcnt lgkmcnt(" #n ")" ::: "memory")
; #define PG8_BAR __builtin_amdgcn_s_barrier()
; #define PG8_SCHED __builtin_amdgcn_sched_barrier(0)
; template <class Epi, class Sched, bool ALIGN_EPI = false, bool SP2 = false>
; __device__ __forceinline__ void gemm_phase(LAS unsigned char* lds, const Gemm g, const Sched& S, const Epi& E, const int tid) {
;     ...
;             PG8_LDB(B0, 0, 0); PG8_LDB(B1, 0, 1); PG8_SCHED; PG8_LDA(At, 0, 0); PG8_STAGE(PG8_SA(1, 1), a1 + hstep, voffA);
;             PG8_WAIT_V(8); PG8_WAIT_L(0); PG8_BAR; PG8_MMA(0, 0, At, B0); PG8_MMA(0, 1, At, B1); PG8_BAR; PG8_SCHED;
;             PG8_LDA(At, 0, 1); PG8_STAGE(PG8_SB(0, 0), b2, voffB); PG8_STAGE(PG8_SB(0, 1), b2 + hstep, voffB); PG8_STAGE(PG8_SA(0, 0), a2, voffA);
;             PG8_WAIT_V(8); PG8_WAIT_L(0); PG8_BAR; PG8_MMA(1, 0, At, B0); PG8_MMA(1, 1, At, B1); PG8_BAR; PG8_SCHED;
.LBB0_367:
	s_add_u32 s4, s0, 0xfff80080
	s_addc_u32 s5, s1, -1
	s_add_i32 s64, 0, 0x10000
	s_cmp_eq_u32 s63, 28
	s_cselect_b32 s39, s7, s5
	s_cselect_b32 s38, s9, s4
	v_add_u32_e32 v144, s64, v189
	s_cselect_b32 s5, s29, s62
	s_cselect_b32 s4, s31, s61
	s_add_i32 s66, 0, 0x14000
	ds_read_b128 v[152:155], v144
	ds_read_b128 v[156:159], v144 offset:1024
	ds_read_b128 v[160:163], v144 offset:2048
	ds_read_b128 v[192:195], v144 offset:3072
	v_add_u32_e32 v144, s66, v189
	ds_read_b128 v[196:199], v144
	ds_read_b128 v[200:203], v144 offset:1024
	ds_read_b128 v[204:207], v144 offset:2048
	ds_read_b128 v[208:211], v144 offset:3072
	v_lshl_add_u64 v[164:165], s[0:1], 0, v[140:141]
	s_add_i32 m0, s50, 0xc000
	ds_read_b128 v[212:215], v190
	ds_read_b128 v[216:219], v190 offset:1024
	ds_read_b128 v[220:223], v190 offset:2048
	ds_read_b128 v[228:231], v190 offset:3072
	ds_read_b128 v[232:235], v190 offset:4096
	ds_read_b128 v[236:239], v190 offset:5120
	ds_read_b128 v[240:243], v190 offset:6144
	ds_read_b128 v[244:247], v190 offset:7168
	global_load_lds_dwordx4 v[164:165], off
	v_lshl_add_u64 v[164:165], s[0:1], 0, v[142:143]
	s_add_i32 m0, s50, 0xe000
	s_nop 0
	global_load_lds_dwordx4 v[164:165], off
	s_waitcnt vmcnt(8)
	s_waitcnt lgkmcnt(0)
	s_barrier
	s_setprio 1
	s_waitcnt lgkmcnt(0)
	v_mfma_f32_16x16x32_bf16 v[124:127], v[152:155], v[212:215], v[124:127]
	v_mfma_f32_16x16x32_bf16 v[120:123], v[160:163], v[212:215], v[120:123]
	v_mfma_f32_16x16x32_bf16 v[108:111], v[152:155], v[220:223], v[108:111]
	v_mfma_f32_16x16x32_bf16 v[104:107], v[160:163], v[220:223], v[104:107]
	v_mfma_f32_16x16x32_bf16 v[92:95], v[152:155], v[232:235], v[92:95]
	v_mfma_f32_16x16x32_bf16 v[88:91], v[160:163], v[232:235], v[88:91]
	v_mfma_f32_16x16x32_bf16 v[76:79], v[152:155], v[240:243], v[76:79]
	v_mfma_f32_16x16x32_bf16 v[72:75], v[160:163], v[240:243], v[72:75]
	v_mfma_f32_16x16x32_bf16 v[124:127], v[156:159], v[216:219], v[124:127]
	v_mfma_f32_16x16x32_bf16 v[120:123], v[192:195], v[216:219], v[120:123]
	v_mfma_f32_16x16x32_bf16 v[108:111], v[156:159], v[228:231], v[108:111]
	v_mfma_f32_16x16x32_bf16 v[104:107], v[192:195], v[228:231], v[104:107]
	v_mfma_f32_16x16x32_bf16 v[92:95], v[156:159], v[236:239], v[92:95]
	v_mfma_f32_16x16x32_bf16 v[88:91], v[192:195], v[236:239], v[88:91]
	v_mfma_f32_16x16x32_bf16 v[76:79], v[156:159], v[244:247], v[76:79]
	v_mfma_f32_16x16x32_bf16 v[72:75], v[192:195], v[244:247], v[72:75]
	s_setprio 0
	s_setprio 1
	v_mfma_f32_16x16x32_bf16 v[116:119], v[196:199], v[212:215], v[116:119]
	v_mfma_f32_16x16x32_bf16 v[112:115], v[204:207], v[212:215], v[112:115]
	v_mfma_f32_16x16x32_bf16 v[100:103], v[196:199], v[220:223], v[100:103]
	v_mfma_f32_16x16x32_bf16 v[96:99], v[204:207], v[220:223], v[96:99]
	v_mfma_f32_16x16x32_bf16 v[84:87], v[196:199], v[232:235], v[84:87]
	v_mfma_f32_16x16x32_bf16 v[80:83], v[204:207], v[232:235], v[80:83]
	v_mfma_f32_16x16x32_bf16 v[68:71], v[196:199], v[240:243], v[68:71]
	v_mfma_f32_16x16x32_bf16 v[64:67], v[204:207], v[240:243], v[64:67]
	v_mfma_f32_16x16x32_bf16 v[116:119], v[200:203], v[216:219], v[116:119]
	v_mfma_f32_16x16x32_bf16 v[112:115], v[208:211], v[216:219], v[112:115]
	v_mfma_f32_16x16x32_bf16 v[100:103], v[200:203], v[228:231], v[100:103]
	v_mfma_f32_16x16x32_bf16 v[96:99], v[208:211], v[228:231], v[96:99]
	v_mfma_f32_16x16x32_bf16 v[84:87], v[200:203], v[236:239], v[84:87]
	v_mfma_f32_16x16x32_bf16 v[80:83], v[208:211], v[236:239], v[80:83]
	v_mfma_f32_16x16x32_bf16 v[68:71], v[200:203], v[244:247], v[68:71]
	v_mfma_f32_16x16x32_bf16 v[64:67], v[208:211], v[244:247], v[64:67]
	s_setprio 0
	s_barrier
	s_add_i32 s64, s64, s45
	v_lshl_add_u64 v[164:165], s[4:5], 0, v[128:129]
	s_mov_b32 m0, s64
	ds_read_b128 v[212:215], v190 offset:16384
	ds_read_b128 v[216:219], v190 offset:17408
	ds_read_b128 v[220:223], v190 offset:18432
	ds_read_b128 v[228:231], v190 offset:19456
	ds_read_b128 v[232:235], v190 offset:20480
	ds_read_b128 v[236:239], v190 offset:21504
	ds_read_b128 v[240:243], v190 offset:22528
	ds_read_b128 v[244:247], v190 offset:23552
	global_load_lds_dwordx4 v[164:165], off
	s_add_i32 m0, s64, 0x2000
	s_add_u32 s64, s4, 0x80000
	v_lshl_add_u64 v[248:249], s[4:5], 0, v[130:131]
	s_addc_u32 s65, s5, 0
	s_add_i32 s66, s66, s45
	global_load_lds_dwordx4 v[248:249], off
	v_lshl_add_u64 v[250:251], s[64:65], 0, v[128:129]
	s_mov_b32 m0, s66
	v_lshl_add_u64 v[252:253], s[38:39], 0, v[130:131]
	global_load_lds_dwordx4 v[250:251], off
	v_lshl_add_u64 v[250:251], s[64:65], 0, v[130:131]
	s_add_i32 m0, s66, 0x2000
	s_nop 0
	global_load_lds_dwordx4 v[250:251], off
	v_lshl_add_u64 v[250:251], s[38:39], 0, v[128:129]
	s_mov_b32 m0, s50
	s_nop 0
	global_load_lds_dwordx4 v[250:251], off
	s_mov_b32 m0, s51
	s_nop 0
	global_load_lds_dwordx4 v[252:253], off
	s_waitcnt vmcnt(8)
	s_waitcnt lgkmcnt(0)
	s_barrier
; #define PG8_STAGE(bufoff, gbase, voff) do { _Pragma("unroll") for (int _i = 0; _i < 2; ++_i) \
;         __builtin_amdgcn_global_load_lds((const unsigned*)((const char*)(gbase) + (voff)[_i]), (LAS unsigned*)(lds + (bufoff) + ldsw + _i * 8192), 16, 0, 0); } while (0)
; #define PG8_LDA(dst, b, h) do { _Pragma("unroll") for (int m = 0; m < 4; ++m) _Pragma("unroll") for (int k = 0; k < 2; ++k) dst[m][k] = *(const LAS bf16x8*)(lds + PG8_SA(b, h) + aoff + m * 2048 + k * 1024); } while (0)
; #define PG8_LDB(dst, b, h) do { _Pragma("unroll") for (int n = 0; n < 2; ++n) _Pragma("unroll") for (int k = 0; k < 2; ++k) dst[n][k] = *(const LAS bf16x8*)(lds + PG8_SB(b, h) + boff + n * 2048 + k * 1024); } while (0)
; #define PG8_MMA(ai, bj, At, Bt) do { __builtin_amdgcn_s_setprio(1); _Pragma("unroll") for (int m = 0; m < 4; ++m) _Pragma("unroll") for (int n = 0; n < 2; ++n) _Pragma("unroll") for (int k = 0; k < 2; ++k) \
;         acc[ai][bj][m][n] = __builtin_amdgcn_mfma_f32_16x16x32_bf16(Bt[n][k], At[m][k], acc[ai][bj][m][n], 0, 0, 0); __builtin_amdgcn_s_setprio(0); } while (0)
; #define PG8_WAIT_V(n) asm volatile("s_waitcnt vmcnt(" #n ")" ::: "memory")
; #define PG8_WAIT_L(n) asm volatile("s_waitcnt lgkmcnt(" #n ")" ::: "memory")
; #define PG8_BAR __builtin_amdgcn_s_barrier()
; #define PG8_SCHED __builtin_amdgcn_sched_barrier(0)
; template <class Epi, class Sched, bool ALIGN_EPI = false, bool SP2 = false>
; __device__ __forceinline__ void gemm_phase(LAS unsigned char* lds, const Gemm g, const Sched& S, const Epi& E, const int tid) {
;     ...
;             PG8_WAIT_V(8); PG8_WAIT_L(0); PG8_BAR; PG8_MMA(1, 0, At, B0); PG8_MMA(1, 1, At, B1); PG8_BAR; PG8_SCHED;
;             PG8_LDB(B0, 1, 0); PG8_LDB(B1, 1, 1); PG8_SCHED; PG8_LDA(At, 1, 0); PG8_STAGE(PG8_SA(0, 1), a2 + hstep, voffA);
;             PG8_WAIT_V(8); PG8_WAIT_L(0); PG8_BAR; PG8_MMA(0, 0, At, B0); PG8_MMA(0, 1, At, B1); PG8_BAR; PG8_SCHED;
;             PG8_LDA(At, 1, 1); PG8_STAGE(PG8_SB(1, 0), b3, voffB); PG8_STAGE(PG8_SB(1, 1), b3 + hstep, voffB); PG8_STAGE(PG8_SA(1, 0), a3, voffA);
	s_setprio 1
	s_waitcnt lgkmcnt(0)
	v_mfma_f32_16x16x32_bf16 v[60:63], v[152:155], v[212:215], v[60:63]
	v_mfma_f32_16x16x32_bf16 v[56:59], v[160:163], v[212:215], v[56:59]
	v_mfma_f32_16x16x32_bf16 v[44:47], v[152:155], v[220:223], v[44:47]
	v_mfma_f32_16x16x32_bf16 v[40:43], v[160:163], v[220:223], v[40:43]
	v_mfma_f32_16x16x32_bf16 v[28:31], v[152:155], v[232:235], v[28:31]
	v_mfma_f32_16x16x32_bf16 v[24:27], v[160:163], v[232:235], v[24:27]
	v_mfma_f32_16x16x32_bf16 v[12:15], v[152:155], v[240:243], v[12:15]
	v_mfma_f32_16x16x32_bf16 v[8:11], v[160:163], v[240:243], v[8:11]
	v_mfma_f32_16x16x32_bf16 v[60:63], v[156:159], v[216:219], v[60:63]
	v_mfma_f32_16x16x32_bf16 v[56:59], v[192:195], v[216:219], v[56:59]
	v_mfma_f32_16x16x32_bf16 v[44:47], v[156:159], v[228:231], v[44:47]
	v_mfma_f32_16x16x32_bf16 v[40:43], v[192:195], v[228:231], v[40:43]
	v_mfma_f32_16x16x32_bf16 v[28:31], v[156:159], v[236:239], v[28:31]
	v_mfma_f32_16x16x32_bf16 v[24:27], v[192:195], v[236:239], v[24:27]
	v_mfma_f32_16x16x32_bf16 v[12:15], v[156:159], v[244:247], v[12:15]
	v_mfma_f32_16x16x32_bf16 v[8:11], v[192:195], v[244:247], v[8:11]
	s_setprio 0
	s_setprio 1
	v_mfma_f32_16x16x32_bf16 v[52:55], v[196:199], v[212:215], v[52:55]
	v_mfma_f32_16x16x32_bf16 v[48:51], v[204:207], v[212:215], v[48:51]
	v_mfma_f32_16x16x32_bf16 v[36:39], v[196:199], v[220:223], v[36:39]
	v_mfma_f32_16x16x32_bf16 v[32:35], v[204:207], v[220:223], v[32:35]
	v_mfma_f32_16x16x32_bf16 v[20:23], v[196:199], v[232:235], v[20:23]
	v_mfma_f32_16x16x32_bf16 v[16:19], v[204:207], v[232:235], v[16:19]
	v_mfma_f32_16x16x32_bf16 v[4:7], v[196:199], v[240:243], v[4:7]
	v_mfma_f32_16x16x32_bf16 v[0:3], v[204:207], v[240:243], v[0:3]
	v_mfma_f32_16x16x32_bf16 v[52:55], v[200:203], v[216:219], v[52:55]
	v_mfma_f32_16x16x32_bf16 v[48:51], v[208:211], v[216:219], v[48:51]
	v_mfma_f32_16x16x32_bf16 v[36:39], v[200:203], v[228:231], v[36:39]
	v_mfma_f32_16x16x32_bf16 v[32:35], v[208:211], v[228:231], v[32:35]
	v_mfma_f32_16x16x32_bf16 v[20:23], v[200:203], v[236:239], v[20:23]
	v_mfma_f32_16x16x32_bf16 v[16:19], v[208:211], v[236:239], v[16:19]
	v_mfma_f32_16x16x32_bf16 v[4:7], v[200:203], v[244:247], v[4:7]
	v_mfma_f32_16x16x32_bf16 v[0:3], v[208:211], v[244:247], v[0:3]
	s_setprio 0
	s_barrier
	s_add_i32 s64, 0, 0x18000
	v_add_u32_e32 v144, s64, v189
	s_add_i32 s65, 0, 0x1c000
	ds_read_b128 v[152:155], v144
	ds_read_b128 v[156:159], v144 offset:1024
	ds_read_b128 v[160:163], v144 offset:2048
	ds_read_b128 v[192:195], v144 offset:3072
	v_add_u32_e32 v144, s65, v189
	ds_read_b128 v[196:199], v144
	ds_read_b128 v[200:203], v144 offset:1024
	ds_read_b128 v[204:207], v144 offset:2048
	ds_read_b128 v[208:211], v144 offset:3072
	s_add_u32 s38, s38, 0x80000
	s_addc_u32 s39, s39, 0
	s_mov_b32 m0, s52
	v_lshl_add_u64 v[150:151], s[38:39], 0, v[128:129]
	ds_read_b128 v[212:215], v190 offset:32768
	ds_read_b128 v[216:219], v190 offset:33792
	ds_read_b128 v[220:223], v190 offset:34816
	ds_read_b128 v[228:231], v190 offset:35840
	ds_read_b128 v[232:235], v190 offset:36864
	ds_read_b128 v[236:239], v190 offset:37888
	ds_read_b128 v[240:243], v190 offset:38912
	ds_read_b128 v[244:247], v190 offset:39936
	global_load_lds_dwordx4 v[150:151], off
	v_lshl_add_u64 v[150:151], s[38:39], 0, v[130:131]
	s_mov_b32 m0, s53
	s_nop 0
	global_load_lds_dwordx4 v[150:151], off
	s_waitcnt vmcnt(8)
	s_waitcnt lgkmcnt(0)
	s_barrier
	s_setprio 1
	s_waitcnt lgkmcnt(0)
	v_mfma_f32_16x16x32_bf16 v[124:127], v[152:155], v[212:215], v[124:127]
	v_mfma_f32_16x16x32_bf16 v[120:123], v[160:163], v[212:215], v[120:123]
	v_mfma_f32_16x16x32_bf16 v[108:111], v[152:155], v[220:223], v[108:111]
	v_mfma_f32_16x16x32_bf16 v[104:107], v[160:163], v[220:223], v[104:107]
	v_mfma_f32_16x16x32_bf16 v[92:95], v[152:155], v[232:235], v[92:95]
	v_mfma_f32_16x16x32_bf16 v[88:91], v[160:163], v[232:235], v[88:91]
	v_mfma_f32_16x16x32_bf16 v[76:79], v[152:155], v[240:243], v[76:79]
	v_mfma_f32_16x16x32_bf16 v[72:75], v[160:163], v[240:243], v[72:75]
	v_mfma_f32_16x16x32_bf16 v[124:127], v[156:159], v[216:219], v[124:127]
	v_mfma_f32_16x16x32_bf16 v[120:123], v[192:195], v[216:219], v[120:123]
	v_mfma_f32_16x16x32_bf16 v[108:111], v[156:159], v[228:231], v[108:111]
	v_mfma_f32_16x16x32_bf16 v[104:107], v[192:195], v[228:231], v[104:107]
	v_mfma_f32_16x16x32_bf16 v[92:95], v[156:159], v[236:239], v[92:95]
	v_mfma_f32_16x16x32_bf16 v[88:91], v[192:195], v[236:239], v[88:91]
	v_mfma_f32_16x16x32_bf16 v[76:79], v[156:159], v[244:247], v[76:79]
	v_mfma_f32_16x16x32_bf16 v[72:75], v[192:195], v[244:247], v[72:75]
	s_setprio 0
	s_setprio 1
	v_mfma_f32_16x16x32_bf16 v[116:119], v[196:199], v[212:215], v[116:119]
	v_mfma_f32_16x16x32_bf16 v[112:115], v[204:207], v[212:215], v[112:115]
	v_mfma_f32_16x16x32_bf16 v[100:103], v[196:199], v[220:223], v[100:103]
	v_mfma_f32_16x16x32_bf16 v[96:99], v[204:207], v[220:223], v[96:99]
	v_mfma_f32_16x16x32_bf16 v[84:87], v[196:199], v[232:235], v[84:87]
	v_mfma_f32_16x16x32_bf16 v[80:83], v[204:207], v[232:235], v[80:83]
	v_mfma_f32_16x16x32_bf16 v[68:71], v[196:199], v[240:243], v[68:71]
	v_mfma_f32_16x16x32_bf16 v[64:67], v[204:207], v[240:243], v[64:67]
	v_mfma_f32_16x16x32_bf16 v[116:119], v[200:203], v[216:219], v[116:119]
	v_mfma_f32_16x16x32_bf16 v[112:115], v[208:211], v[216:219], v[112:115]
	v_mfma_f32_16x16x32_bf16 v[100:103], v[200:203], v[228:231], v[100:103]
	v_mfma_f32_16x16x32_bf16 v[96:99], v[208:211], v[228:231], v[96:99]
	v_mfma_f32_16x16x32_bf16 v[84:87], v[200:203], v[236:239], v[84:87]
	v_mfma_f32_16x16x32_bf16 v[80:83], v[208:211], v[236:239], v[80:83]
	v_mfma_f32_16x16x32_bf16 v[68:71], v[200:203], v[244:247], v[68:71]
	v_mfma_f32_16x16x32_bf16 v[64:67], v[208:211], v[244:247], v[64:67]
	s_setprio 0
	s_barrier
; #define PG8_STAGE(bufoff, gbase, voff) do { _Pragma("unroll") for (int _i = 0; _i < 2; ++_i) \
;         __builtin_amdgcn_global_load_lds((const unsigned*)((const char*)(gbase) + (voff)[_i]), (LAS unsigned*)(lds + (bufoff) + ldsw + _i * 8192), 16, 0, 0); } while (0)
; #define PG8_LDA(dst, b, h) do { _Pragma("unroll") for (int m = 0; m < 4; ++m) _Pragma("unroll") for (int k = 0; k < 2; ++k) dst[m][k] = *(const LAS bf16x8*)(lds + PG8_SA(b, h) + aoff + m * 2048 + k * 1024); } while (0)
; #define PG8_MMA(ai, bj, At, Bt) do { __builtin_amdgcn_s_setprio(1); _Pragma("unroll") for (int m = 0; m < 4; ++m) _Pragma("unroll") for (int n = 0; n < 2; ++n) _Pragma("unroll") for (int k = 0; k < 2; ++k) \
;         acc[ai][bj][m][n] = __builtin_amdgcn_mfma_f32_16x16x32_bf16(Bt[n][k], At[m][k], acc[ai][bj][m][n], 0, 0, 0); __builtin_amdgcn_s_setprio(0); } while (0)
; #define PG8_WAIT_V(n) asm volatile("s_waitcnt vmcnt(" #n ")" ::: "memory")
; #define PG8_WAIT_L(n) asm volatile("s_waitcnt lgkmcnt(" #n ")" ::: "memory")
; #define PG8_BAR __builtin_amdgcn_s_barrier()
; #define PG8_SCHED __builtin_amdgcn_sched_barrier(0)
; template <class Epi, class Sched, bool ALIGN_EPI = false, bool SP2 = false>
; __device__ __forceinline__ void gemm_phase(LAS unsigned char* lds, const Gemm g, const Sched& S, const Epi& E, const int tid) {
;     ...
;         for (int t = 0; t < nt; t += 2) {
;     ...
;             PG8_LDA(At, 1, 1); PG8_STAGE(PG8_SB(1, 0), b3, voffB); PG8_STAGE(PG8_SB(1, 1), b3 + hstep, voffB); PG8_STAGE(PG8_SA(1, 0), a3, voffA);
;             PG8_WAIT_V(8); PG8_WAIT_L(0); PG8_BAR; PG8_MMA(1, 0, At, B0); PG8_MMA(1, 1, At, B1); PG8_BAR; PG8_SCHED;
	s_add_i32 s38, s64, s45
	v_lshl_add_u64 v[150:151], v[164:165], 0, s[70:71]
	s_mov_b32 m0, s38
	ds_read_b128 v[212:215], v190 offset:49152
	ds_read_b128 v[216:219], v190 offset:50176
	ds_read_b128 v[220:223], v190 offset:51200
	ds_read_b128 v[228:231], v190 offset:52224
	ds_read_b128 v[232:235], v190 offset:53248
	ds_read_b128 v[236:239], v190 offset:54272
	ds_read_b128 v[240:243], v190 offset:55296
	ds_read_b128 v[244:247], v190 offset:56320
	global_load_lds_dwordx4 v[150:151], off
	s_add_i32 m0, s38, 0x2000
	s_add_u32 s4, s4, 0x80080
	v_lshl_add_u64 v[150:151], v[248:249], 0, s[70:71]
	s_addc_u32 s5, s5, 0
	s_add_i32 s38, s65, s45
	global_load_lds_dwordx4 v[150:151], off
	v_lshl_add_u64 v[150:151], s[4:5], 0, v[128:129]
	s_mov_b32 m0, s38
	s_nop 0
	global_load_lds_dwordx4 v[150:151], off
	v_lshl_add_u64 v[150:151], s[4:5], 0, v[130:131]
	s_add_i32 m0, s38, 0x2000
	s_nop 0
	global_load_lds_dwordx4 v[150:151], off
	v_lshl_add_u64 v[150:151], v[250:251], 0, s[70:71]
	s_mov_b32 m0, s55
	s_nop 0
	global_load_lds_dwordx4 v[150:151], off
	v_lshl_add_u64 v[150:151], v[252:253], 0, s[70:71]
	s_mov_b32 m0, s56
	s_nop 0
	global_load_lds_dwordx4 v[150:151], off
	s_waitcnt vmcnt(8)
	s_waitcnt lgkmcnt(0)
	s_barrier
	s_setprio 1
	s_waitcnt lgkmcnt(0)
	v_mfma_f32_16x16x32_bf16 v[60:63], v[152:155], v[212:215], v[60:63]
	v_mfma_f32_16x16x32_bf16 v[56:59], v[160:163], v[212:215], v[56:59]
	v_mfma_f32_16x16x32_bf16 v[44:47], v[152:155], v[220:223], v[44:47]
	v_mfma_f32_16x16x32_bf16 v[40:43], v[160:163], v[220:223], v[40:43]
	v_mfma_f32_16x16x32_bf16 v[28:31], v[152:155], v[232:235], v[28:31]
	v_mfma_f32_16x16x32_bf16 v[24:27], v[160:163], v[232:235], v[24:27]
	v_mfma_f32_16x16x32_bf16 v[12:15], v[152:155], v[240:243], v[12:15]
	v_mfma_f32_16x16x32_bf16 v[8:11], v[160:163], v[240:243], v[8:11]
	v_mfma_f32_16x16x32_bf16 v[60:63], v[156:159], v[216:219], v[60:63]
	v_mfma_f32_16x16x32_bf16 v[56:59], v[192:195], v[216:219], v[56:59]
	v_mfma_f32_16x16x32_bf16 v[44:47], v[156:159], v[228:231], v[44:47]
	v_mfma_f32_16x16x32_bf16 v[40:43], v[192:195], v[228:231], v[40:43]
	v_mfma_f32_16x16x32_bf16 v[28:31], v[156:159], v[236:239], v[28:31]
	v_mfma_f32_16x16x32_bf16 v[24:27], v[192:195], v[236:239], v[24:27]
	v_mfma_f32_16x16x32_bf16 v[12:15], v[156:159], v[244:247], v[12:15]
	v_mfma_f32_16x16x32_bf16 v[8:11], v[192:195], v[244:247], v[8:11]
	s_setprio 0
	s_setprio 1
	v_mfma_f32_16x16x32_bf16 v[52:55], v[196:199], v[212:215], v[52:55]
	v_mfma_f32_16x16x32_bf16 v[48:51], v[204:207], v[212:215], v[48:51]
	v_mfma_f32_16x16x32_bf16 v[36:39], v[196:199], v[220:223], v[36:39]
	v_mfma_f32_16x16x32_bf16 v[32:35], v[204:207], v[220:223], v[32:35]
	v_mfma_f32_16x16x32_bf16 v[20:23], v[196:199], v[232:235], v[20:23]
	v_mfma_f32_16x16x32_bf16 v[16:19], v[204:207], v[232:235], v[16:19]
	v_mfma_f32_16x16x32_bf16 v[4:7], v[196:199], v[240:243], v[4:7]
	v_mfma_f32_16x16x32_bf16 v[0:3], v[204:207], v[240:243], v[0:3]
	v_mfma_f32_16x16x32_bf16 v[52:55], v[200:203], v[216:219], v[52:55]
	v_mfma_f32_16x16x32_bf16 v[48:51], v[208:211], v[216:219], v[48:51]
	v_mfma_f32_16x16x32_bf16 v[36:39], v[200:203], v[228:231], v[36:39]
	v_mfma_f32_16x16x32_bf16 v[32:35], v[208:211], v[228:231], v[32:35]
	v_mfma_f32_16x16x32_bf16 v[20:23], v[200:203], v[236:239], v[20:23]
	v_mfma_f32_16x16x32_bf16 v[16:19], v[208:211], v[236:239], v[16:19]
	v_mfma_f32_16x16x32_bf16 v[4:7], v[200:203], v[244:247], v[4:7]
	v_mfma_f32_16x16x32_bf16 v[0:3], v[208:211], v[244:247], v[0:3]
	s_setprio 0
	s_add_i32 s63, s63, 2
	s_add_u32 s0, s0, 0x100
	s_addc_u32 s1, s1, 0
	s_add_u32 s61, s61, 0x100
	s_addc_u32 s62, s62, 0
	s_cmp_gt_u32 s63, 29
	s_barrier
	s_cbranch_scc0 .LBB0_367
	s_and_b64 vcc, exec, s[14:15]
	s_cbranch_vccz .LBB0_370
	s_barrier

; #define PG8_STAGE(bufoff, gbase, voff) do { _Pragma("unroll") for (int _i = 0; _i < 2; ++_i) \
;         __builtin_amdgcn_global_load_lds((const unsigned*)((const char*)(gbase) + (voff)[_i]), (LAS unsigned*)(lds + (bufoff) + ldsw + _i * 8192), 16, 0, 0); } while (0)
; #define PG8_LDA(dst, b, h) do { _Pragma("unroll") for (int m = 0; m < 4; ++m) _Pragma("unroll") for (int k = 0; k < 2; ++k) dst[m][k] = *(const LAS bf16x8*)(lds + PG8_SA(b, h) + aoff + m * 2048 + k * 1024); } while (0)
; #define PG8_LDB(dst, b, h) do { _Pragma("unroll") for (int n = 0; n < 2; ++n) _Pragma("unroll") for (int k = 0; k < 2; ++k) dst[n][k] = *(const LAS bf16x8*)(lds + PG8_SB(b, h) + boff + n * 2048 + k * 1024); } while (0)
; #define PG8_MMA(ai, bj, At, Bt) do { __builtin_amdgcn_s_setprio(1); _Pragma("unroll") for (int m = 0; m < 4; ++m) _Pragma("unroll") for (int n = 0; n < 2; ++n) _Pragma("unroll") for (int k = 0; k < 2; ++k) \
;         acc[ai][bj][m][n] = __builtin_amdgcn_mfma_f32_16x16x32_bf16(Bt[n][k], At[m][k], acc[ai][bj][m][n], 0, 0, 0); __builtin_amdgcn_s_setprio(0); } while (0)
; #define PG8_WAIT_V(n) asm volatile("s_waitcnt vmcnt(" #n ")" ::: "memory")
; #define PG8_WAIT_L(n) asm volatile("s_waitcnt lgkmcnt(" #n ")" ::: "memory")
; #define PG8_BAR __builtin_amdgcn_s_barrier()
; #define PG8_SCHED __builtin_amdgcn_sched_barrier(0)
; template <class Epi, class Sched, bool ALIGN_EPI = false, bool SP2 = false>
; __device__ __forceinline__ void gemm_phase(LAS unsigned char* lds, const Gemm g, const Sched& S, const Epi& E, const int tid) {
;     ...
;             PG8_LDB(B0, 0, 0); PG8_LDB(B1, 0, 1); PG8_SCHED; PG8_LDA(At, 0, 0); PG8_STAGE(PG8_SA(1, 1), a1 + hstep, voffA);
;             PG8_WAIT_V(8); PG8_WAIT_L(0); PG8_BAR; PG8_MMA(0, 0, At, B0); PG8_MMA(0, 1, At, B1); PG8_BAR; PG8_SCHED;
;             PG8_LDA(At, 0, 1); PG8_STAGE(PG8_SB(0, 0), b2, voffB); PG8_STAGE(PG8_SB(0, 1), b2 + hstep, voffB); PG8_STAGE(PG8_SA(0, 0), a2, voffA);
;             PG8_WAIT_V(8); PG8_WAIT_L(0); PG8_BAR; PG8_MMA(1, 0, At, B0); PG8_MMA(1, 1, At, B1); PG8_BAR; PG8_SCHED;
.LBB0_1315:
	s_add_u32 s24, s22, 0xfffc0080
	s_addc_u32 s25, s23, -1
	s_add_i32 s51, 0, 0x10000
	s_cmp_eq_u32 s50, 12
	s_cselect_b32 s27, s17, s25
	s_cselect_b32 s26, s46, s24
	s_cselect_b32 s25, s15, s49
	s_cselect_b32 s24, s47, s48
	s_add_i32 s54, 0, 0x14000
	v_add_u32_e32 v92, s51, v165
	v_add_u32_e32 v150, s54, v165
	ds_read_b128 v[72:75], v92
	ds_read_b128 v[76:79], v92 offset:1024
	ds_read_b128 v[88:91], v92 offset:2048
	ds_read_b128 v[92:95], v92 offset:3072
	ds_read_b128 v[158:161], v150
	ds_read_b128 v[190:193], v150 offset:1024
	ds_read_b128 v[194:197], v150 offset:2048
	ds_read_b128 v[198:201], v150 offset:3072
	v_lshl_add_u64 v[150:151], s[22:23], 0, v[154:155]
	s_add_i32 m0, s38, 0xc000
	ds_read_b128 v[202:205], v189
	ds_read_b128 v[206:209], v189 offset:1024
	ds_read_b128 v[210:213], v189 offset:2048
	ds_read_b128 v[214:217], v189 offset:3072
	ds_read_b128 v[218:221], v189 offset:4096
	ds_read_b128 v[228:231], v189 offset:5120
	ds_read_b128 v[232:235], v189 offset:6144
	ds_read_b128 v[236:239], v189 offset:7168
	global_load_lds_dwordx4 v[150:151], off
	v_lshl_add_u64 v[150:151], s[22:23], 0, v[156:157]
	s_add_i32 m0, s38, 0xe000
	s_nop 0
	global_load_lds_dwordx4 v[150:151], off
	s_waitcnt vmcnt(8)
	s_waitcnt lgkmcnt(0)
	s_barrier
	s_setprio 1
	s_waitcnt lgkmcnt(0)
	v_mfma_f32_16x16x32_bf16 v[140:143], v[72:75], v[202:205], v[140:143]
	v_mfma_f32_16x16x32_bf16 v[136:139], v[88:91], v[202:205], v[136:139]
	v_mfma_f32_16x16x32_bf16 v[124:127], v[72:75], v[210:213], v[124:127]
	v_mfma_f32_16x16x32_bf16 v[120:123], v[88:91], v[210:213], v[120:123]
	v_mfma_f32_16x16x32_bf16 v[108:111], v[72:75], v[218:221], v[108:111]
	v_mfma_f32_16x16x32_bf16 v[104:107], v[88:91], v[218:221], v[104:107]
	v_mfma_f32_16x16x32_bf16 v[84:87], v[72:75], v[232:235], v[84:87]
	v_mfma_f32_16x16x32_bf16 v[80:83], v[88:91], v[232:235], v[80:83]
	v_mfma_f32_16x16x32_bf16 v[140:143], v[76:79], v[206:209], v[140:143]
	v_mfma_f32_16x16x32_bf16 v[136:139], v[92:95], v[206:209], v[136:139]
	v_mfma_f32_16x16x32_bf16 v[124:127], v[76:79], v[214:217], v[124:127]
	v_mfma_f32_16x16x32_bf16 v[120:123], v[92:95], v[214:217], v[120:123]
	v_mfma_f32_16x16x32_bf16 v[108:111], v[76:79], v[228:231], v[108:111]
	v_mfma_f32_16x16x32_bf16 v[104:107], v[92:95], v[228:231], v[104:107]
	v_mfma_f32_16x16x32_bf16 v[84:87], v[76:79], v[236:239], v[84:87]
	v_mfma_f32_16x16x32_bf16 v[80:83], v[92:95], v[236:239], v[80:83]
	s_setprio 0
	s_setprio 1
	v_mfma_f32_16x16x32_bf16 v[132:135], v[158:161], v[202:205], v[132:135]
	v_mfma_f32_16x16x32_bf16 v[128:131], v[194:197], v[202:205], v[128:131]
	v_mfma_f32_16x16x32_bf16 v[112:115], v[158:161], v[210:213], v[112:115]
	v_mfma_f32_16x16x32_bf16 v[116:119], v[194:197], v[210:213], v[116:119]
	v_mfma_f32_16x16x32_bf16 v[96:99], v[158:161], v[218:221], v[96:99]
	v_mfma_f32_16x16x32_bf16 v[100:103], v[194:197], v[218:221], v[100:103]
	v_mfma_f32_16x16x32_bf16 v[64:67], v[158:161], v[232:235], v[64:67]
	v_mfma_f32_16x16x32_bf16 v[68:71], v[194:197], v[232:235], v[68:71]
	v_mfma_f32_16x16x32_bf16 v[132:135], v[190:193], v[206:209], v[132:135]
	v_mfma_f32_16x16x32_bf16 v[128:131], v[198:201], v[206:209], v[128:131]
	v_mfma_f32_16x16x32_bf16 v[112:115], v[190:193], v[214:217], v[112:115]
	v_mfma_f32_16x16x32_bf16 v[116:119], v[198:201], v[214:217], v[116:119]
	v_mfma_f32_16x16x32_bf16 v[96:99], v[190:193], v[228:231], v[96:99]
	v_mfma_f32_16x16x32_bf16 v[100:103], v[198:201], v[228:231], v[100:103]
	v_mfma_f32_16x16x32_bf16 v[64:67], v[190:193], v[236:239], v[64:67]
	v_mfma_f32_16x16x32_bf16 v[68:71], v[198:201], v[236:239], v[68:71]
	s_setprio 0
	s_barrier
	s_add_i32 s51, s51, s37
	v_lshl_add_u64 v[150:151], s[24:25], 0, v[144:145]
	s_mov_b32 m0, s51
	ds_read_b128 v[202:205], v189 offset:16384
	ds_read_b128 v[206:209], v189 offset:17408
	ds_read_b128 v[210:213], v189 offset:18432
	ds_read_b128 v[214:217], v189 offset:19456
	ds_read_b128 v[218:221], v189 offset:20480
	ds_read_b128 v[228:231], v189 offset:21504
	ds_read_b128 v[232:235], v189 offset:22528
	ds_read_b128 v[236:239], v189 offset:23552
	global_load_lds_dwordx4 v[150:151], off
	s_add_i32 m0, s51, 0x2000
	s_add_u32 s52, s24, 0x40000
	v_lshl_add_u64 v[162:163], s[24:25], 0, v[152:153]
	s_addc_u32 s53, s25, 0
	s_add_i32 s51, s54, s37
	global_load_lds_dwordx4 v[162:163], off
	v_lshl_add_u64 v[222:223], s[52:53], 0, v[144:145]
	s_mov_b32 m0, s51
	v_lshl_add_u64 v[240:241], s[26:27], 0, v[152:153]
	global_load_lds_dwordx4 v[222:223], off
	v_lshl_add_u64 v[222:223], s[52:53], 0, v[152:153]
	s_add_i32 m0, s51, 0x2000
	s_nop 0
	global_load_lds_dwordx4 v[222:223], off
	v_lshl_add_u64 v[222:223], s[26:27], 0, v[144:145]
	s_mov_b32 m0, s38
	s_nop 0
	global_load_lds_dwordx4 v[222:223], off
	s_mov_b32 m0, s39
	s_nop 0
	global_load_lds_dwordx4 v[240:241], off
	s_waitcnt vmcnt(8)
	s_waitcnt lgkmcnt(0)
	s_barrier
; #define PG8_STAGE(bufoff, gbase, voff) do { _Pragma("unroll") for (int _i = 0; _i < 2; ++_i) \
;         __builtin_amdgcn_global_load_lds((const unsigned*)((const char*)(gbase) + (voff)[_i]), (LAS unsigned*)(lds + (bufoff) + ldsw + _i * 8192), 16, 0, 0); } while (0)
; #define PG8_LDA(dst, b, h) do { _Pragma("unroll") for (int m = 0; m < 4; ++m) _Pragma("unroll") for (int k = 0; k < 2; ++k) dst[m][k] = *(const LAS bf16x8*)(lds + PG8_SA(b, h) + aoff + m * 2048 + k * 1024); } while (0)
; #define PG8_LDB(dst, b, h) do { _Pragma("unroll") for (int n = 0; n < 2; ++n) _Pragma("unroll") for (int k = 0; k < 2; ++k) dst[n][k] = *(const LAS bf16x8*)(lds + PG8_SB(b, h) + boff + n * 2048 + k * 1024); } while (0)
; #define PG8_MMA(ai, bj, At, Bt) do { __builtin_amdgcn_s_setprio(1); _Pragma("unroll") for (int m = 0; m < 4; ++m) _Pragma("unroll") for (int n = 0; n < 2; ++n) _Pragma("unroll") for (int k = 0; k < 2; ++k) \
;         acc[ai][bj][m][n] = __builtin_amdgcn_mfma_f32_16x16x32_bf16(Bt[n][k], At[m][k], acc[ai][bj][m][n], 0, 0, 0); __builtin_amdgcn_s_setprio(0); } while (0)
; #define PG8_WAIT_V(n) asm volatile("s_waitcnt vmcnt(" #n ")" ::: "memory")
; #define PG8_WAIT_L(n) asm volatile("s_waitcnt lgkmcnt(" #n ")" ::: "memory")
; #define PG8_BAR __builtin_amdgcn_s_barrier()
; #define PG8_SCHED __builtin_amdgcn_sched_barrier(0)
; template <class Epi, class Sched, bool ALIGN_EPI = false, bool SP2 = false>
; __device__ __forceinline__ void gemm_phase(LAS unsigned char* lds, const Gemm g, const Sched& S, const Epi& E, const int tid) {
;     ...
;             PG8_WAIT_V(8); PG8_WAIT_L(0); PG8_BAR; PG8_MMA(1, 0, At, B0); PG8_MMA(1, 1, At, B1); PG8_BAR; PG8_SCHED;
;             PG8_LDB(B0, 1, 0); PG8_LDB(B1, 1, 1); PG8_SCHED; PG8_LDA(At, 1, 0); PG8_STAGE(PG8_SA(0, 1), a2 + hstep, voffA);
;             PG8_WAIT_V(8); PG8_WAIT_L(0); PG8_BAR; PG8_MMA(0, 0, At, B0); PG8_MMA(0, 1, At, B1); PG8_BAR; PG8_SCHED;
	s_setprio 1
	s_waitcnt lgkmcnt(0)
	v_mfma_f32_16x16x32_bf16 v[60:63], v[72:75], v[202:205], v[60:63]
	v_mfma_f32_16x16x32_bf16 v[56:59], v[88:91], v[202:205], v[56:59]
	v_mfma_f32_16x16x32_bf16 v[44:47], v[72:75], v[210:213], v[44:47]
	v_mfma_f32_16x16x32_bf16 v[40:43], v[88:91], v[210:213], v[40:43]
	v_mfma_f32_16x16x32_bf16 v[28:31], v[72:75], v[218:221], v[28:31]
	v_mfma_f32_16x16x32_bf16 v[24:27], v[88:91], v[218:221], v[24:27]
	v_mfma_f32_16x16x32_bf16 v[12:15], v[72:75], v[232:235], v[12:15]
	v_mfma_f32_16x16x32_bf16 v[8:11], v[88:91], v[232:235], v[8:11]
	v_mfma_f32_16x16x32_bf16 v[60:63], v[76:79], v[206:209], v[60:63]
	v_mfma_f32_16x16x32_bf16 v[56:59], v[92:95], v[206:209], v[56:59]
	v_mfma_f32_16x16x32_bf16 v[44:47], v[76:79], v[214:217], v[44:47]
	v_mfma_f32_16x16x32_bf16 v[40:43], v[92:95], v[214:217], v[40:43]
	v_mfma_f32_16x16x32_bf16 v[28:31], v[76:79], v[228:231], v[28:31]
	v_mfma_f32_16x16x32_bf16 v[24:27], v[92:95], v[228:231], v[24:27]
	v_mfma_f32_16x16x32_bf16 v[12:15], v[76:79], v[236:239], v[12:15]
	v_mfma_f32_16x16x32_bf16 v[8:11], v[92:95], v[236:239], v[8:11]
	s_setprio 0
	s_setprio 1
	v_mfma_f32_16x16x32_bf16 v[48:51], v[158:161], v[202:205], v[48:51]
	v_mfma_f32_16x16x32_bf16 v[52:55], v[194:197], v[202:205], v[52:55]
	v_mfma_f32_16x16x32_bf16 v[32:35], v[158:161], v[210:213], v[32:35]
	v_mfma_f32_16x16x32_bf16 v[36:39], v[194:197], v[210:213], v[36:39]
	v_mfma_f32_16x16x32_bf16 v[16:19], v[158:161], v[218:221], v[16:19]
	v_mfma_f32_16x16x32_bf16 v[20:23], v[194:197], v[218:221], v[20:23]
	v_mfma_f32_16x16x32_bf16 v[0:3], v[158:161], v[232:235], v[0:3]
	v_mfma_f32_16x16x32_bf16 v[4:7], v[194:197], v[232:235], v[4:7]
	v_mfma_f32_16x16x32_bf16 v[48:51], v[190:193], v[206:209], v[48:51]
	v_mfma_f32_16x16x32_bf16 v[52:55], v[198:201], v[206:209], v[52:55]
	v_mfma_f32_16x16x32_bf16 v[32:35], v[190:193], v[214:217], v[32:35]
	v_mfma_f32_16x16x32_bf16 v[36:39], v[198:201], v[214:217], v[36:39]
	v_mfma_f32_16x16x32_bf16 v[16:19], v[190:193], v[228:231], v[16:19]
	v_mfma_f32_16x16x32_bf16 v[20:23], v[198:201], v[228:231], v[20:23]
	v_mfma_f32_16x16x32_bf16 v[0:3], v[190:193], v[236:239], v[0:3]
	v_mfma_f32_16x16x32_bf16 v[4:7], v[198:201], v[236:239], v[4:7]
	s_setprio 0
	s_barrier
	s_add_i32 s51, 0, 0x18000
	s_add_i32 s52, 0, 0x1c000
	v_add_u32_e32 v92, s51, v165
	v_add_u32_e32 v198, s52, v165
	ds_read_b128 v[72:75], v92
	ds_read_b128 v[76:79], v92 offset:1024
	ds_read_b128 v[88:91], v92 offset:2048
	ds_read_b128 v[92:95], v92 offset:3072
	ds_read_b128 v[158:161], v198
	ds_read_b128 v[190:193], v198 offset:1024
	ds_read_b128 v[194:197], v198 offset:2048
	ds_read_b128 v[198:201], v198 offset:3072
	s_add_u32 s26, s26, 0x40000
	s_addc_u32 s27, s27, 0
	s_mov_b32 m0, s40
	v_lshl_add_u64 v[242:243], s[26:27], 0, v[144:145]
	ds_read_b128 v[202:205], v189 offset:32768
	ds_read_b128 v[206:209], v189 offset:33792
	ds_read_b128 v[210:213], v189 offset:34816
	ds_read_b128 v[214:217], v189 offset:35840
	ds_read_b128 v[218:221], v189 offset:36864
	ds_read_b128 v[228:231], v189 offset:37888
	ds_read_b128 v[232:235], v189 offset:38912
	ds_read_b128 v[236:239], v189 offset:39936
	global_load_lds_dwordx4 v[242:243], off
	v_lshl_add_u64 v[242:243], s[26:27], 0, v[152:153]
	s_mov_b32 m0, s41
	s_nop 0
	global_load_lds_dwordx4 v[242:243], off
	s_waitcnt vmcnt(8)
	s_waitcnt lgkmcnt(0)
	s_barrier
	s_setprio 1
	s_waitcnt lgkmcnt(0)
	v_mfma_f32_16x16x32_bf16 v[140:143], v[72:75], v[202:205], v[140:143]
	v_mfma_f32_16x16x32_bf16 v[136:139], v[88:91], v[202:205], v[136:139]
	v_mfma_f32_16x16x32_bf16 v[124:127], v[72:75], v[210:213], v[124:127]
	v_mfma_f32_16x16x32_bf16 v[120:123], v[88:91], v[210:213], v[120:123]
	v_mfma_f32_16x16x32_bf16 v[108:111], v[72:75], v[218:221], v[108:111]
	v_mfma_f32_16x16x32_bf16 v[104:107], v[88:91], v[218:221], v[104:107]
	v_mfma_f32_16x16x32_bf16 v[84:87], v[72:75], v[232:235], v[84:87]
	v_mfma_f32_16x16x32_bf16 v[80:83], v[88:91], v[232:235], v[80:83]
	v_mfma_f32_16x16x32_bf16 v[140:143], v[76:79], v[206:209], v[140:143]
	v_mfma_f32_16x16x32_bf16 v[136:139], v[92:95], v[206:209], v[136:139]
	v_mfma_f32_16x16x32_bf16 v[124:127], v[76:79], v[214:217], v[124:127]
	v_mfma_f32_16x16x32_bf16 v[120:123], v[92:95], v[214:217], v[120:123]
	v_mfma_f32_16x16x32_bf16 v[108:111], v[76:79], v[228:231], v[108:111]
	v_mfma_f32_16x16x32_bf16 v[104:107], v[92:95], v[228:231], v[104:107]
	v_mfma_f32_16x16x32_bf16 v[84:87], v[76:79], v[236:239], v[84:87]
	v_mfma_f32_16x16x32_bf16 v[80:83], v[92:95], v[236:239], v[80:83]
	s_setprio 0
	s_setprio 1
	v_mfma_f32_16x16x32_bf16 v[132:135], v[158:161], v[202:205], v[132:135]
	v_mfma_f32_16x16x32_bf16 v[128:131], v[194:197], v[202:205], v[128:131]
	v_mfma_f32_16x16x32_bf16 v[112:115], v[158:161], v[210:213], v[112:115]
	v_mfma_f32_16x16x32_bf16 v[116:119], v[194:197], v[210:213], v[116:119]
	v_mfma_f32_16x16x32_bf16 v[96:99], v[158:161], v[218:221], v[96:99]
	v_mfma_f32_16x16x32_bf16 v[100:103], v[194:197], v[218:221], v[100:103]
	v_mfma_f32_16x16x32_bf16 v[64:67], v[158:161], v[232:235], v[64:67]
	v_mfma_f32_16x16x32_bf16 v[68:71], v[194:197], v[232:235], v[68:71]
	v_mfma_f32_16x16x32_bf16 v[132:135], v[190:193], v[206:209], v[132:135]
	v_mfma_f32_16x16x32_bf16 v[128:131], v[198:201], v[206:209], v[128:131]
	v_mfma_f32_16x16x32_bf16 v[112:115], v[190:193], v[214:217], v[112:115]
	v_mfma_f32_16x16x32_bf16 v[116:119], v[198:201], v[214:217], v[116:119]
	v_mfma_f32_16x16x32_bf16 v[96:99], v[190:193], v[228:231], v[96:99]
	v_mfma_f32_16x16x32_bf16 v[100:103], v[198:201], v[228:231], v[100:103]
	v_mfma_f32_16x16x32_bf16 v[64:67], v[190:193], v[236:239], v[64:67]
	v_mfma_f32_16x16x32_bf16 v[68:71], v[198:201], v[236:239], v[68:71]
	s_setprio 0
	s_barrier
; #define PG8_STAGE(bufoff, gbase, voff) do { _Pragma("unroll") for (int _i = 0; _i < 2; ++_i) \
;         __builtin_amdgcn_global_load_lds((const unsigned*)((const char*)(gbase) + (voff)[_i]), (LAS unsigned*)(lds + (bufoff) + ldsw + _i * 8192), 16, 0, 0); } while (0)
; #define PG8_LDA(dst, b, h) do { _Pragma("unroll") for (int m = 0; m < 4; ++m) _Pragma("unroll") for (int k = 0; k < 2; ++k) dst[m][k] = *(const LAS bf16x8*)(lds + PG8_SA(b, h) + aoff + m * 2048 + k * 1024); } while (0)
; #define PG8_MMA(ai, bj, At, Bt) do { __builtin_amdgcn_s_setprio(1); _Pragma("unroll") for (int m = 0; m < 4; ++m) _Pragma("unroll") for (int n = 0; n < 2; ++n) _Pragma("unroll") for (int k = 0; k < 2; ++k) \
;         acc[ai][bj][m][n] = __builtin_amdgcn_mfma_f32_16x16x32_bf16(Bt[n][k], At[m][k], acc[ai][bj][m][n], 0, 0, 0); __builtin_amdgcn_s_setprio(0); } while (0)
; #define PG8_WAIT_V(n) asm volatile("s_waitcnt vmcnt(" #n ")" ::: "memory")
; #define PG8_WAIT_L(n) asm volatile("s_waitcnt lgkmcnt(" #n ")" ::: "memory")
; #define PG8_BAR __builtin_amdgcn_s_barrier()
; #define PG8_SCHED __builtin_amdgcn_sched_barrier(0)
; template <class Epi, class Sched, bool ALIGN_EPI = false, bool SP2 = false>
; __device__ __forceinline__ void gemm_phase(LAS unsigned char* lds, const Gemm g, const Sched& S, const Epi& E, const int tid) {
;     ...
;         for (int t = 0; t < nt; t += 2) {
;             const bool last = (t == nt - 2);
;             const char* a1 = cA + (size_t)(t + 1) * kstep;
;             const char* a2 = last ? nA : cA + (size_t)(t + 2) * kstep; const char* b2 = last ? nB : cB + (size_t)(t + 2) * kstep;
;             const char* a3 = a2 + kstep; const char* b3 = b2 + kstep;
;     ...
;             PG8_LDA(At, 1, 1); PG8_STAGE(PG8_SB(1, 0), b3, voffB); PG8_STAGE(PG8_SB(1, 1), b3 + hstep, voffB); PG8_STAGE(PG8_SA(1, 0), a3, voffA);
;             PG8_WAIT_V(8); PG8_WAIT_L(0); PG8_BAR; PG8_MMA(1, 0, At, B0); PG8_MMA(1, 1, At, B1); PG8_BAR; PG8_SCHED;
	s_add_i32 s26, s51, s37
	v_lshl_add_u64 v[150:151], v[150:151], 0, s[70:71]
	s_mov_b32 m0, s26
	ds_read_b128 v[202:205], v189 offset:49152
	ds_read_b128 v[206:209], v189 offset:50176
	ds_read_b128 v[210:213], v189 offset:51200
	ds_read_b128 v[214:217], v189 offset:52224
	ds_read_b128 v[218:221], v189 offset:53248
	ds_read_b128 v[228:231], v189 offset:54272
	ds_read_b128 v[232:235], v189 offset:55296
	ds_read_b128 v[236:239], v189 offset:56320
	global_load_lds_dwordx4 v[150:151], off
	s_add_i32 m0, s26, 0x2000
	s_add_u32 s24, s24, 0x40080
	v_lshl_add_u64 v[150:151], v[162:163], 0, s[70:71]
	s_addc_u32 s25, s25, 0
	s_add_i32 s26, s52, s37
	global_load_lds_dwordx4 v[150:151], off
	v_lshl_add_u64 v[150:151], s[24:25], 0, v[144:145]
	s_mov_b32 m0, s26
	s_nop 0
	global_load_lds_dwordx4 v[150:151], off
	v_lshl_add_u64 v[150:151], s[24:25], 0, v[152:153]
	s_add_i32 m0, s26, 0x2000
	s_nop 0
	global_load_lds_dwordx4 v[150:151], off
	v_lshl_add_u64 v[150:151], v[222:223], 0, s[70:71]
	s_mov_b32 m0, s42
	s_nop 0
	global_load_lds_dwordx4 v[150:151], off
	v_lshl_add_u64 v[150:151], v[240:241], 0, s[70:71]
	s_mov_b32 m0, s43
	s_nop 0
	global_load_lds_dwordx4 v[150:151], off
	s_waitcnt vmcnt(8)
	s_waitcnt lgkmcnt(0)
	s_barrier
	s_setprio 1
	s_waitcnt lgkmcnt(0)
	v_mfma_f32_16x16x32_bf16 v[60:63], v[72:75], v[202:205], v[60:63]
	v_mfma_f32_16x16x32_bf16 v[56:59], v[88:91], v[202:205], v[56:59]
	v_mfma_f32_16x16x32_bf16 v[44:47], v[72:75], v[210:213], v[44:47]
	v_mfma_f32_16x16x32_bf16 v[40:43], v[88:91], v[210:213], v[40:43]
	v_mfma_f32_16x16x32_bf16 v[28:31], v[72:75], v[218:221], v[28:31]
	v_mfma_f32_16x16x32_bf16 v[24:27], v[88:91], v[218:221], v[24:27]
	v_mfma_f32_16x16x32_bf16 v[12:15], v[72:75], v[232:235], v[12:15]
	v_mfma_f32_16x16x32_bf16 v[8:11], v[88:91], v[232:235], v[8:11]
	v_mfma_f32_16x16x32_bf16 v[60:63], v[76:79], v[206:209], v[60:63]
	v_mfma_f32_16x16x32_bf16 v[56:59], v[92:95], v[206:209], v[56:59]
	v_mfma_f32_16x16x32_bf16 v[44:47], v[76:79], v[214:217], v[44:47]
	v_mfma_f32_16x16x32_bf16 v[40:43], v[92:95], v[214:217], v[40:43]
	v_mfma_f32_16x16x32_bf16 v[28:31], v[76:79], v[228:231], v[28:31]
	v_mfma_f32_16x16x32_bf16 v[24:27], v[92:95], v[228:231], v[24:27]
	v_mfma_f32_16x16x32_bf16 v[12:15], v[76:79], v[236:239], v[12:15]
	v_mfma_f32_16x16x32_bf16 v[8:11], v[92:95], v[236:239], v[8:11]
	s_setprio 0
	s_setprio 1
	v_mfma_f32_16x16x32_bf16 v[48:51], v[158:161], v[202:205], v[48:51]
	v_mfma_f32_16x16x32_bf16 v[52:55], v[194:197], v[202:205], v[52:55]
	v_mfma_f32_16x16x32_bf16 v[32:35], v[158:161], v[210:213], v[32:35]
	v_mfma_f32_16x16x32_bf16 v[36:39], v[194:197], v[210:213], v[36:39]
	v_mfma_f32_16x16x32_bf16 v[16:19], v[158:161], v[218:221], v[16:19]
	v_mfma_f32_16x16x32_bf16 v[20:23], v[194:197], v[218:221], v[20:23]
	v_mfma_f32_16x16x32_bf16 v[0:3], v[158:161], v[232:235], v[0:3]
	v_mfma_f32_16x16x32_bf16 v[4:7], v[194:197], v[232:235], v[4:7]
	v_mfma_f32_16x16x32_bf16 v[48:51], v[190:193], v[206:209], v[48:51]
	v_mfma_f32_16x16x32_bf16 v[52:55], v[198:201], v[206:209], v[52:55]
	v_mfma_f32_16x16x32_bf16 v[32:35], v[190:193], v[214:217], v[32:35]
	v_mfma_f32_16x16x32_bf16 v[36:39], v[198:201], v[214:217], v[36:39]
	v_mfma_f32_16x16x32_bf16 v[16:19], v[190:193], v[228:231], v[16:19]
	v_mfma_f32_16x16x32_bf16 v[20:23], v[198:201], v[228:231], v[20:23]
	v_mfma_f32_16x16x32_bf16 v[0:3], v[190:193], v[236:239], v[0:3]
	v_mfma_f32_16x16x32_bf16 v[4:7], v[198:201], v[236:239], v[4:7]
	s_setprio 0
	s_add_i32 s50, s50, 2
	s_add_u32 s22, s22, 0x100
	s_addc_u32 s23, s23, 0
	s_add_u32 s48, s48, 0x100
	s_addc_u32 s49, s49, 0
	s_cmp_gt_u32 s50, 13
	s_barrier
	s_cbranch_scc0 .LBB0_1315
	s_and_b64 vcc, exec, s[10:11]
	s_cbranch_vccz .LBB0_1318
	s_barrier

; #define PG8_STAGE(bufoff, gbase, voff) do { _Pragma("unroll") for (int _i = 0; _i < 2; ++_i) \
;         __builtin_amdgcn_global_load_lds((const unsigned*)((const char*)(gbase) + (voff)[_i]), (LAS unsigned*)(lds + (bufoff) + ldsw + _i * 8192), 16, 0, 0); } while (0)
; #define PG8_LDA(dst, b, h) do { _Pragma("unroll") for (int m = 0; m < 4; ++m) _Pragma("unroll") for (int k = 0; k < 2; ++k) dst[m][k] = *(const LAS bf16x8*)(lds + PG8_SA(b, h) + aoff + m * 2048 + k * 1024); } while (0)
; #define PG8_LDB(dst, b, h) do { _Pragma("unroll") for (int n = 0; n < 2; ++n) _Pragma("unroll") for (int k = 0; k < 2; ++k) dst[n][k] = *(const LAS bf16x8*)(lds + PG8_SB(b, h) + boff + n * 2048 + k * 1024); } while (0)
; #define PG8_MMA(ai, bj, At, Bt) do { __builtin_amdgcn_s_setprio(1); _Pragma("unroll") for (int m = 0; m < 4; ++m) _Pragma("unroll") for (int n = 0; n < 2; ++n) _Pragma("unroll") for (int k = 0; k < 2; ++k) \
;         acc[ai][bj][m][n] = __builtin_amdgcn_mfma_f32_16x16x32_bf16(Bt[n][k], At[m][k], acc[ai][bj][m][n], 0, 0, 0); __builtin_amdgcn_s_setprio(0); } while (0)
; #define PG8_WAIT_V(n) asm volatile("s_waitcnt vmcnt(" #n ")" ::: "memory")
; #define PG8_WAIT_L(n) asm volatile("s_waitcnt lgkmcnt(" #n ")" ::: "memory")
; template <class Epi, class Sched, bool ALIGN_EPI = false, bool SP2 = false>
; __device__ __forceinline__ void gemm_phase(LAS unsigned char* lds, const Gemm g, const Sched& S, const Epi& E, const int tid) {
;     ...
;         const char* nA = has_next ? (const char*)g.A + (size_t)nxt.pm * tstep : cA; const char* nB = has_next ? (const char*)g.Bt + (size_t)nxt.pn * tstep : cB;
;         for (int t = 0; t < nt; t += 2) {
;             const bool last = (t == nt - 2);
;             const char* a1 = cA + (size_t)(t + 1) * kstep;
;             const char* a2 = last ? nA : cA + (size_t)(t + 2) * kstep; const char* b2 = last ? nB : cB + (size_t)(t + 2) * kstep;
;             const char* a3 = a2 + kstep; const char* b3 = b2 + kstep;
;             if constexpr (SP2) {
;             PG8_LDB(B0, 0, 0); PG8_LDB(B1, 0, 1); PG8_SCHED; PG8_LDA(At, 0, 0); PG8_STAGE(PG8_SA(1, 1), a1 + hstep, voffA);
;             PG8_WAIT_V(8); PG8_WAIT_L(0); PG8_BAR; PG8_MMA(0, 0, At, B0); PG8_MMA(0, 1, At, B1); PG8_BAR; PG8_SCHED;
;             PG8_LDA(At, 0, 1); PG8_STAGE(PG8_SB(0, 0), b2, voffB); PG8_STAGE(PG8_SB(0, 1), b2 + hstep, voffB); PG8_STAGE(PG8_SA(0, 0), a2, voffA);
.LBB0_1355:
	s_add_u32 s24, s22, 0x100
	s_addc_u32 s25, s23, 0
	s_add_i32 s54, 0, 0x10000
	s_cmp_eq_u32 s53, 28
	s_cselect_b32 s29, s1, s25
	s_cselect_b32 s28, s15, s24
	v_add_u32_e32 v138, s54, v141
	s_cselect_b32 s27, s13, s52
	s_cselect_b32 s26, s21, s51
	s_add_i32 s55, 0, 0x14000
	ds_read_b128 v[134:137], v138
	ds_read_b128 v[152:155], v138 offset:1024
	ds_read_b128 v[156:159], v138 offset:2048
	ds_read_b128 v[160:163], v138 offset:3072
	v_add_u32_e32 v138, s55, v141
	ds_read_b128 v[188:191], v138
	ds_read_b128 v[192:195], v138 offset:1024
	ds_read_b128 v[196:199], v138 offset:2048
	ds_read_b128 v[200:203], v138 offset:3072
	v_lshl_add_u64 v[138:139], s[22:23], 0, v[130:131]
	s_add_i32 m0, s39, 0xc000
	ds_read_b128 v[204:207], v143
	ds_read_b128 v[208:211], v143 offset:1024
	ds_read_b128 v[212:215], v143 offset:2048
	ds_read_b128 v[216:219], v143 offset:3072
	ds_read_b128 v[220:223], v143 offset:4096
	ds_read_b128 v[228:231], v143 offset:5120
	ds_read_b128 v[232:235], v143 offset:6144
	ds_read_b128 v[236:239], v143 offset:7168
	global_load_lds_dwordx4 v[138:139], off
	v_lshl_add_u64 v[138:139], s[22:23], 0, v[132:133]
	s_add_i32 m0, s39, 0xe000
	s_nop 0
	global_load_lds_dwordx4 v[138:139], off
	s_waitcnt vmcnt(8)
	s_waitcnt lgkmcnt(0)
	s_barrier
	s_setprio 1
	s_waitcnt lgkmcnt(0)
	v_mfma_f32_16x16x32_bf16 v[124:127], v[134:137], v[204:207], v[124:127]
	v_mfma_f32_16x16x32_bf16 v[120:123], v[156:159], v[204:207], v[120:123]
	v_mfma_f32_16x16x32_bf16 v[108:111], v[134:137], v[212:215], v[108:111]
	v_mfma_f32_16x16x32_bf16 v[104:107], v[156:159], v[212:215], v[104:107]
	v_mfma_f32_16x16x32_bf16 v[92:95], v[134:137], v[220:223], v[92:95]
	v_mfma_f32_16x16x32_bf16 v[88:91], v[156:159], v[220:223], v[88:91]
	v_mfma_f32_16x16x32_bf16 v[76:79], v[134:137], v[232:235], v[76:79]
	v_mfma_f32_16x16x32_bf16 v[72:75], v[156:159], v[232:235], v[72:75]
	v_mfma_f32_16x16x32_bf16 v[124:127], v[152:155], v[208:211], v[124:127]
	v_mfma_f32_16x16x32_bf16 v[120:123], v[160:163], v[208:211], v[120:123]
	v_mfma_f32_16x16x32_bf16 v[108:111], v[152:155], v[216:219], v[108:111]
	v_mfma_f32_16x16x32_bf16 v[104:107], v[160:163], v[216:219], v[104:107]
	v_mfma_f32_16x16x32_bf16 v[92:95], v[152:155], v[228:231], v[92:95]
	v_mfma_f32_16x16x32_bf16 v[88:91], v[160:163], v[228:231], v[88:91]
	v_mfma_f32_16x16x32_bf16 v[76:79], v[152:155], v[236:239], v[76:79]
	v_mfma_f32_16x16x32_bf16 v[72:75], v[160:163], v[236:239], v[72:75]
	s_setprio 0
	s_setprio 1
	v_mfma_f32_16x16x32_bf16 v[116:119], v[188:191], v[204:207], v[116:119]
	v_mfma_f32_16x16x32_bf16 v[112:115], v[196:199], v[204:207], v[112:115]
	v_mfma_f32_16x16x32_bf16 v[100:103], v[188:191], v[212:215], v[100:103]
	v_mfma_f32_16x16x32_bf16 v[96:99], v[196:199], v[212:215], v[96:99]
	v_mfma_f32_16x16x32_bf16 v[84:87], v[188:191], v[220:223], v[84:87]
	v_mfma_f32_16x16x32_bf16 v[80:83], v[196:199], v[220:223], v[80:83]
	v_mfma_f32_16x16x32_bf16 v[68:71], v[188:191], v[232:235], v[68:71]
	v_mfma_f32_16x16x32_bf16 v[64:67], v[196:199], v[232:235], v[64:67]
	v_mfma_f32_16x16x32_bf16 v[116:119], v[192:195], v[208:211], v[116:119]
	v_mfma_f32_16x16x32_bf16 v[112:115], v[200:203], v[208:211], v[112:115]
	v_mfma_f32_16x16x32_bf16 v[100:103], v[192:195], v[216:219], v[100:103]
	v_mfma_f32_16x16x32_bf16 v[96:99], v[200:203], v[216:219], v[96:99]
	v_mfma_f32_16x16x32_bf16 v[84:87], v[192:195], v[228:231], v[84:87]
	v_mfma_f32_16x16x32_bf16 v[80:83], v[200:203], v[228:231], v[80:83]
	v_mfma_f32_16x16x32_bf16 v[68:71], v[192:195], v[236:239], v[68:71]
	v_mfma_f32_16x16x32_bf16 v[64:67], v[200:203], v[236:239], v[64:67]
	s_setprio 0
	s_barrier
	s_add_i32 s22, s54, s38
	v_lshl_add_u64 v[138:139], s[26:27], 0, v[144:145]
	s_mov_b32 m0, s22
	ds_read_b128 v[204:207], v143 offset:16384
	ds_read_b128 v[208:211], v143 offset:17408
	ds_read_b128 v[212:215], v143 offset:18432
	ds_read_b128 v[216:219], v143 offset:19456
	ds_read_b128 v[220:223], v143 offset:20480
	ds_read_b128 v[228:231], v143 offset:21504
	ds_read_b128 v[232:235], v143 offset:22528
	ds_read_b128 v[236:239], v143 offset:23552
	global_load_lds_dwordx4 v[138:139], off
	s_add_i32 m0, s22, 0x2000
	s_add_u32 s22, s26, 0x80000
	v_lshl_add_u64 v[150:151], s[26:27], 0, v[128:129]
	s_addc_u32 s23, s27, 0
	s_add_i32 s54, s55, s38
	global_load_lds_dwordx4 v[150:151], off
	v_lshl_add_u64 v[164:165], s[22:23], 0, v[144:145]
	s_mov_b32 m0, s54
	v_lshl_add_u64 v[240:241], s[28:29], 0, v[128:129]
	global_load_lds_dwordx4 v[164:165], off
	v_lshl_add_u64 v[164:165], s[22:23], 0, v[128:129]
	s_add_i32 m0, s54, 0x2000
	s_nop 0
	global_load_lds_dwordx4 v[164:165], off
	v_lshl_add_u64 v[164:165], s[28:29], 0, v[144:145]
	s_mov_b32 m0, s39
	s_nop 0
	global_load_lds_dwordx4 v[164:165], off
	s_mov_b32 m0, s40
	s_nop 0
	global_load_lds_dwordx4 v[240:241], off
	s_waitcnt vmcnt(8)
	s_waitcnt lgkmcnt(0)
	s_barrier
; #define PG8_STAGE(bufoff, gbase, voff) do { _Pragma("unroll") for (int _i = 0; _i < 2; ++_i) \
;         __builtin_amdgcn_global_load_lds((const unsigned*)((const char*)(gbase) + (voff)[_i]), (LAS unsigned*)(lds + (bufoff) + ldsw + _i * 8192), 16, 0, 0); } while (0)
; #define PG8_LDA(dst, b, h) do { _Pragma("unroll") for (int m = 0; m < 4; ++m) _Pragma("unroll") for (int k = 0; k < 2; ++k) dst[m][k] = *(const LAS bf16x8*)(lds + PG8_SA(b, h) + aoff + m * 2048 + k * 1024); } while (0)
; #define PG8_LDB(dst, b, h) do { _Pragma("unroll") for (int n = 0; n < 2; ++n) _Pragma("unroll") for (int k = 0; k < 2; ++k) dst[n][k] = *(const LAS bf16x8*)(lds + PG8_SB(b, h) + boff + n * 2048 + k * 1024); } while (0)
; #define PG8_MMA(ai, bj, At, Bt) do { __builtin_amdgcn_s_setprio(1); _Pragma("unroll") for (int m = 0; m < 4; ++m) _Pragma("unroll") for (int n = 0; n < 2; ++n) _Pragma("unroll") for (int k = 0; k < 2; ++k) \
;         acc[ai][bj][m][n] = __builtin_amdgcn_mfma_f32_16x16x32_bf16(Bt[n][k], At[m][k], acc[ai][bj][m][n], 0, 0, 0); __builtin_amdgcn_s_setprio(0); } while (0)
; #define PG8_WAIT_V(n) asm volatile("s_waitcnt vmcnt(" #n ")" ::: "memory")
; #define PG8_WAIT_L(n) asm volatile("s_waitcnt lgkmcnt(" #n ")" ::: "memory")
; #define PG8_BAR __builtin_amdgcn_s_barrier()
; #define PG8_SCHED __builtin_amdgcn_sched_barrier(0)
; template <class Epi, class Sched, bool ALIGN_EPI = false, bool SP2 = false>
; __device__ __forceinline__ void gemm_phase(LAS unsigned char* lds, const Gemm g, const Sched& S, const Epi& E, const int tid) {
;     ...
;             PG8_WAIT_V(8); PG8_WAIT_L(0); PG8_BAR; PG8_MMA(1, 0, At, B0); PG8_MMA(1, 1, At, B1); PG8_BAR; PG8_SCHED;
;             PG8_LDB(B0, 1, 0); PG8_LDB(B1, 1, 1); PG8_SCHED; PG8_LDA(At, 1, 0); PG8_STAGE(PG8_SA(0, 1), a2 + hstep, voffA);
;             PG8_WAIT_V(8); PG8_WAIT_L(0); PG8_BAR; PG8_MMA(0, 0, At, B0); PG8_MMA(0, 1, At, B1); PG8_BAR; PG8_SCHED;
	s_setprio 1
	s_waitcnt lgkmcnt(0)
	v_mfma_f32_16x16x32_bf16 v[60:63], v[134:137], v[204:207], v[60:63]
	v_mfma_f32_16x16x32_bf16 v[56:59], v[156:159], v[204:207], v[56:59]
	v_mfma_f32_16x16x32_bf16 v[44:47], v[134:137], v[212:215], v[44:47]
	v_mfma_f32_16x16x32_bf16 v[40:43], v[156:159], v[212:215], v[40:43]
	v_mfma_f32_16x16x32_bf16 v[28:31], v[134:137], v[220:223], v[28:31]
	v_mfma_f32_16x16x32_bf16 v[24:27], v[156:159], v[220:223], v[24:27]
	v_mfma_f32_16x16x32_bf16 v[12:15], v[134:137], v[232:235], v[12:15]
	v_mfma_f32_16x16x32_bf16 v[8:11], v[156:159], v[232:235], v[8:11]
	v_mfma_f32_16x16x32_bf16 v[60:63], v[152:155], v[208:211], v[60:63]
	v_mfma_f32_16x16x32_bf16 v[56:59], v[160:163], v[208:211], v[56:59]
	v_mfma_f32_16x16x32_bf16 v[44:47], v[152:155], v[216:219], v[44:47]
	v_mfma_f32_16x16x32_bf16 v[40:43], v[160:163], v[216:219], v[40:43]
	v_mfma_f32_16x16x32_bf16 v[28:31], v[152:155], v[228:231], v[28:31]
	v_mfma_f32_16x16x32_bf16 v[24:27], v[160:163], v[228:231], v[24:27]
	v_mfma_f32_16x16x32_bf16 v[12:15], v[152:155], v[236:239], v[12:15]
	v_mfma_f32_16x16x32_bf16 v[8:11], v[160:163], v[236:239], v[8:11]
	s_setprio 0
	s_setprio 1
	v_mfma_f32_16x16x32_bf16 v[52:55], v[188:191], v[204:207], v[52:55]
	v_mfma_f32_16x16x32_bf16 v[48:51], v[196:199], v[204:207], v[48:51]
	v_mfma_f32_16x16x32_bf16 v[36:39], v[188:191], v[212:215], v[36:39]
	v_mfma_f32_16x16x32_bf16 v[32:35], v[196:199], v[212:215], v[32:35]
	v_mfma_f32_16x16x32_bf16 v[20:23], v[188:191], v[220:223], v[20:23]
	v_mfma_f32_16x16x32_bf16 v[16:19], v[196:199], v[220:223], v[16:19]
	v_mfma_f32_16x16x32_bf16 v[4:7], v[188:191], v[232:235], v[4:7]
	v_mfma_f32_16x16x32_bf16 v[0:3], v[196:199], v[232:235], v[0:3]
	v_mfma_f32_16x16x32_bf16 v[52:55], v[192:195], v[208:211], v[52:55]
	v_mfma_f32_16x16x32_bf16 v[48:51], v[200:203], v[208:211], v[48:51]
	v_mfma_f32_16x16x32_bf16 v[36:39], v[192:195], v[216:219], v[36:39]
	v_mfma_f32_16x16x32_bf16 v[32:35], v[200:203], v[216:219], v[32:35]
	v_mfma_f32_16x16x32_bf16 v[20:23], v[192:195], v[228:231], v[20:23]
	v_mfma_f32_16x16x32_bf16 v[16:19], v[200:203], v[228:231], v[16:19]
	v_mfma_f32_16x16x32_bf16 v[4:7], v[192:195], v[236:239], v[4:7]
	v_mfma_f32_16x16x32_bf16 v[0:3], v[200:203], v[236:239], v[0:3]
	s_setprio 0
	s_barrier
	s_add_i32 s54, 0, 0x18000
	s_add_i32 s55, 0, 0x1c000
	v_add_u32_e32 v160, s54, v141
	v_add_u32_e32 v200, s55, v141
	ds_read_b128 v[134:137], v160
	ds_read_b128 v[152:155], v160 offset:1024
	ds_read_b128 v[156:159], v160 offset:2048
	ds_read_b128 v[160:163], v160 offset:3072
	ds_read_b128 v[188:191], v200
	ds_read_b128 v[192:195], v200 offset:1024
	ds_read_b128 v[196:199], v200 offset:2048
	ds_read_b128 v[200:203], v200 offset:3072
	s_add_u32 s22, s28, 0x80000
	s_addc_u32 s23, s29, 0
	s_mov_b32 m0, s41
	v_lshl_add_u64 v[242:243], s[22:23], 0, v[144:145]
	ds_read_b128 v[204:207], v143 offset:32768
	ds_read_b128 v[208:211], v143 offset:33792
	ds_read_b128 v[212:215], v143 offset:34816
	ds_read_b128 v[216:219], v143 offset:35840
	ds_read_b128 v[220:223], v143 offset:36864
	ds_read_b128 v[228:231], v143 offset:37888
	ds_read_b128 v[232:235], v143 offset:38912
	ds_read_b128 v[236:239], v143 offset:39936
	global_load_lds_dwordx4 v[242:243], off
	v_lshl_add_u64 v[242:243], s[22:23], 0, v[128:129]
	s_mov_b32 m0, s42
	s_nop 0
	global_load_lds_dwordx4 v[242:243], off
	s_waitcnt vmcnt(8)
	s_waitcnt lgkmcnt(0)
	s_barrier
	s_setprio 1
	s_waitcnt lgkmcnt(0)
	v_mfma_f32_16x16x32_bf16 v[124:127], v[134:137], v[204:207], v[124:127]
	v_mfma_f32_16x16x32_bf16 v[120:123], v[156:159], v[204:207], v[120:123]
	v_mfma_f32_16x16x32_bf16 v[108:111], v[134:137], v[212:215], v[108:111]
	v_mfma_f32_16x16x32_bf16 v[104:107], v[156:159], v[212:215], v[104:107]
	v_mfma_f32_16x16x32_bf16 v[92:95], v[134:137], v[220:223], v[92:95]
	v_mfma_f32_16x16x32_bf16 v[88:91], v[156:159], v[220:223], v[88:91]
	v_mfma_f32_16x16x32_bf16 v[76:79], v[134:137], v[232:235], v[76:79]
	v_mfma_f32_16x16x32_bf16 v[72:75], v[156:159], v[232:235], v[72:75]
	v_mfma_f32_16x16x32_bf16 v[124:127], v[152:155], v[208:211], v[124:127]
	v_mfma_f32_16x16x32_bf16 v[120:123], v[160:163], v[208:211], v[120:123]
	v_mfma_f32_16x16x32_bf16 v[108:111], v[152:155], v[216:219], v[108:111]
	v_mfma_f32_16x16x32_bf16 v[104:107], v[160:163], v[216:219], v[104:107]
	v_mfma_f32_16x16x32_bf16 v[92:95], v[152:155], v[228:231], v[92:95]
	v_mfma_f32_16x16x32_bf16 v[88:91], v[160:163], v[228:231], v[88:91]
	v_mfma_f32_16x16x32_bf16 v[76:79], v[152:155], v[236:239], v[76:79]
	v_mfma_f32_16x16x32_bf16 v[72:75], v[160:163], v[236:239], v[72:75]
	s_setprio 0
	s_setprio 1
	v_mfma_f32_16x16x32_bf16 v[116:119], v[188:191], v[204:207], v[116:119]
	v_mfma_f32_16x16x32_bf16 v[112:115], v[196:199], v[204:207], v[112:115]
	v_mfma_f32_16x16x32_bf16 v[100:103], v[188:191], v[212:215], v[100:103]
	v_mfma_f32_16x16x32_bf16 v[96:99], v[196:199], v[212:215], v[96:99]
	v_mfma_f32_16x16x32_bf16 v[84:87], v[188:191], v[220:223], v[84:87]
	v_mfma_f32_16x16x32_bf16 v[80:83], v[196:199], v[220:223], v[80:83]
	v_mfma_f32_16x16x32_bf16 v[68:71], v[188:191], v[232:235], v[68:71]
	v_mfma_f32_16x16x32_bf16 v[64:67], v[196:199], v[232:235], v[64:67]
	v_mfma_f32_16x16x32_bf16 v[116:119], v[192:195], v[208:211], v[116:119]
	v_mfma_f32_16x16x32_bf16 v[112:115], v[200:203], v[208:211], v[112:115]
	v_mfma_f32_16x16x32_bf16 v[100:103], v[192:195], v[216:219], v[100:103]
	v_mfma_f32_16x16x32_bf16 v[96:99], v[200:203], v[216:219], v[96:99]
	v_mfma_f32_16x16x32_bf16 v[84:87], v[192:195], v[228:231], v[84:87]
	v_mfma_f32_16x16x32_bf16 v[80:83], v[200:203], v[228:231], v[80:83]
	v_mfma_f32_16x16x32_bf16 v[68:71], v[192:195], v[236:239], v[68:71]
	v_mfma_f32_16x16x32_bf16 v[64:67], v[200:203], v[236:239], v[64:67]
	s_setprio 0
	s_barrier
; #define PG8_STAGE(bufoff, gbase, voff) do { _Pragma("unroll") for (int _i = 0; _i < 2; ++_i) \
;         __builtin_amdgcn_global_load_lds((const unsigned*)((const char*)(gbase) + (voff)[_i]), (LAS unsigned*)(lds + (bufoff) + ldsw + _i * 8192), 16, 0, 0); } while (0)
; #define PG8_LDA(dst, b, h) do { _Pragma("unroll") for (int m = 0; m < 4; ++m) _Pragma("unroll") for (int k = 0; k < 2; ++k) dst[m][k] = *(const LAS bf16x8*)(lds + PG8_SA(b, h) + aoff + m * 2048 + k * 1024); } while (0)
; #define PG8_MMA(ai, bj, At, Bt) do { __builtin_amdgcn_s_setprio(1); _Pragma("unroll") for (int m = 0; m < 4; ++m) _Pragma("unroll") for (int n = 0; n < 2; ++n) _Pragma("unroll") for (int k = 0; k < 2; ++k) \
;         acc[ai][bj][m][n] = __builtin_amdgcn_mfma_f32_16x16x32_bf16(Bt[n][k], At[m][k], acc[ai][bj][m][n], 0, 0, 0); __builtin_amdgcn_s_setprio(0); } while (0)
; #define PG8_WAIT_V(n) asm volatile("s_waitcnt vmcnt(" #n ")" ::: "memory")
; #define PG8_WAIT_L(n) asm volatile("s_waitcnt lgkmcnt(" #n ")" ::: "memory")
; #define PG8_BAR __builtin_amdgcn_s_barrier()
; #define PG8_SCHED __builtin_amdgcn_sched_barrier(0)
; template <class Epi, class Sched, bool ALIGN_EPI = false, bool SP2 = false>
; __device__ __forceinline__ void gemm_phase(LAS unsigned char* lds, const Gemm g, const Sched& S, const Epi& E, const int tid) {
;     ...
;         for (int t = 0; t < nt; t += 2) {
;             const bool last = (t == nt - 2);
;             const char* a1 = cA + (size_t)(t + 1) * kstep;
;             const char* a2 = last ? nA : cA + (size_t)(t + 2) * kstep; const char* b2 = last ? nB : cB + (size_t)(t + 2) * kstep;
;             const char* a3 = a2 + kstep; const char* b3 = b2 + kstep;
;     ...
;             PG8_LDA(At, 1, 1); PG8_STAGE(PG8_SB(1, 0), b3, voffB); PG8_STAGE(PG8_SB(1, 1), b3 + hstep, voffB); PG8_STAGE(PG8_SA(1, 0), a3, voffA);
;             PG8_WAIT_V(8); PG8_WAIT_L(0); PG8_BAR; PG8_MMA(1, 0, At, B0); PG8_MMA(1, 1, At, B1); PG8_BAR; PG8_SCHED;
	s_add_i32 s22, s54, s38
	v_lshl_add_u64 v[138:139], v[138:139], 0, s[70:71]
	s_mov_b32 m0, s22
	ds_read_b128 v[204:207], v143 offset:49152
	ds_read_b128 v[208:211], v143 offset:50176
	ds_read_b128 v[212:215], v143 offset:51200
	ds_read_b128 v[216:219], v143 offset:52224
	ds_read_b128 v[220:223], v143 offset:53248
	ds_read_b128 v[228:231], v143 offset:54272
	ds_read_b128 v[232:235], v143 offset:55296
	ds_read_b128 v[236:239], v143 offset:56320
	global_load_lds_dwordx4 v[138:139], off
	s_add_i32 m0, s22, 0x2000
	s_add_u32 s22, s26, 0x80080
	v_lshl_add_u64 v[138:139], v[150:151], 0, s[70:71]
	s_addc_u32 s23, s27, 0
	s_add_i32 s26, s55, s38
	global_load_lds_dwordx4 v[138:139], off
	v_lshl_add_u64 v[138:139], s[22:23], 0, v[144:145]
	s_mov_b32 m0, s26
	s_nop 0
	global_load_lds_dwordx4 v[138:139], off
	v_lshl_add_u64 v[138:139], s[22:23], 0, v[128:129]
	s_add_i32 m0, s26, 0x2000
	s_nop 0
	global_load_lds_dwordx4 v[138:139], off
	v_lshl_add_u64 v[138:139], v[164:165], 0, s[70:71]
	s_mov_b32 m0, s46
	s_nop 0
	global_load_lds_dwordx4 v[138:139], off
	v_lshl_add_u64 v[138:139], v[240:241], 0, s[70:71]
	s_mov_b32 m0, s47
	s_nop 0
	global_load_lds_dwordx4 v[138:139], off
	s_waitcnt vmcnt(8)
	s_waitcnt lgkmcnt(0)
	s_barrier
	s_setprio 1
	s_waitcnt lgkmcnt(0)
	v_mfma_f32_16x16x32_bf16 v[60:63], v[134:137], v[204:207], v[60:63]
	v_mfma_f32_16x16x32_bf16 v[56:59], v[156:159], v[204:207], v[56:59]
	v_mfma_f32_16x16x32_bf16 v[44:47], v[134:137], v[212:215], v[44:47]
	v_mfma_f32_16x16x32_bf16 v[40:43], v[156:159], v[212:215], v[40:43]
	v_mfma_f32_16x16x32_bf16 v[28:31], v[134:137], v[220:223], v[28:31]
	v_mfma_f32_16x16x32_bf16 v[24:27], v[156:159], v[220:223], v[24:27]
	v_mfma_f32_16x16x32_bf16 v[12:15], v[134:137], v[232:235], v[12:15]
	v_mfma_f32_16x16x32_bf16 v[8:11], v[156:159], v[232:235], v[8:11]
	v_mfma_f32_16x16x32_bf16 v[60:63], v[152:155], v[208:211], v[60:63]
	v_mfma_f32_16x16x32_bf16 v[56:59], v[160:163], v[208:211], v[56:59]
	v_mfma_f32_16x16x32_bf16 v[44:47], v[152:155], v[216:219], v[44:47]
	v_mfma_f32_16x16x32_bf16 v[40:43], v[160:163], v[216:219], v[40:43]
	v_mfma_f32_16x16x32_bf16 v[28:31], v[152:155], v[228:231], v[28:31]
	v_mfma_f32_16x16x32_bf16 v[24:27], v[160:163], v[228:231], v[24:27]
	v_mfma_f32_16x16x32_bf16 v[12:15], v[152:155], v[236:239], v[12:15]
	v_mfma_f32_16x16x32_bf16 v[8:11], v[160:163], v[236:239], v[8:11]
	s_setprio 0
	s_setprio 1
	v_mfma_f32_16x16x32_bf16 v[52:55], v[188:191], v[204:207], v[52:55]
	v_mfma_f32_16x16x32_bf16 v[48:51], v[196:199], v[204:207], v[48:51]
	v_mfma_f32_16x16x32_bf16 v[36:39], v[188:191], v[212:215], v[36:39]
	v_mfma_f32_16x16x32_bf16 v[32:35], v[196:199], v[212:215], v[32:35]
	v_mfma_f32_16x16x32_bf16 v[20:23], v[188:191], v[220:223], v[20:23]
	v_mfma_f32_16x16x32_bf16 v[16:19], v[196:199], v[220:223], v[16:19]
	v_mfma_f32_16x16x32_bf16 v[4:7], v[188:191], v[232:235], v[4:7]
	v_mfma_f32_16x16x32_bf16 v[0:3], v[196:199], v[232:235], v[0:3]
	v_mfma_f32_16x16x32_bf16 v[52:55], v[192:195], v[208:211], v[52:55]
	v_mfma_f32_16x16x32_bf16 v[48:51], v[200:203], v[208:211], v[48:51]
	v_mfma_f32_16x16x32_bf16 v[36:39], v[192:195], v[216:219], v[36:39]
	v_mfma_f32_16x16x32_bf16 v[32:35], v[200:203], v[216:219], v[32:35]
	v_mfma_f32_16x16x32_bf16 v[20:23], v[192:195], v[228:231], v[20:23]
	v_mfma_f32_16x16x32_bf16 v[16:19], v[200:203], v[228:231], v[16:19]
	v_mfma_f32_16x16x32_bf16 v[4:7], v[192:195], v[236:239], v[4:7]
	v_mfma_f32_16x16x32_bf16 v[0:3], v[200:203], v[236:239], v[0:3]
	s_setprio 0
	s_add_i32 s53, s53, 2
	s_add_u32 s51, s51, 0x100
	s_addc_u32 s52, s52, 0
	s_cmp_gt_u32 s53, 29
	s_mov_b64 s[22:23], s[24:25]
	s_barrier
	s_cbranch_scc0 .LBB0_1355
	s_and_b64 vcc, exec, s[10:11]
	s_cbranch_vccz .LBB0_1358
	s_barrier

; #define PG8_STAGE(bufoff, gbase, voff) do { _Pragma("unroll") for (int _i = 0; _i < 2; ++_i) \
;         __builtin_amdgcn_global_load_lds((const unsigned*)((const char*)(gbase) + (voff)[_i]), (LAS unsigned*)(lds + (bufoff) + ldsw + _i * 8192), 16, 0, 0); } while (0)
; #define PG8_LDA(dst, b, h) do { _Pragma("unroll") for (int m = 0; m < 4; ++m) _Pragma("unroll") for (int k = 0; k < 2; ++k) dst[m][k] = *(const LAS bf16x8*)(lds + PG8_SA(b, h) + aoff + m * 2048 + k * 1024); } while (0)
; #define PG8_LDB(dst, b, h) do { _Pragma("unroll") for (int n = 0; n < 2; ++n) _Pragma("unroll") for (int k = 0; k < 2; ++k) dst[n][k] = *(const LAS bf16x8*)(lds + PG8_SB(b, h) + boff + n * 2048 + k * 1024); } while (0)
; #define PG8_MMA(ai, bj, At, Bt) do { __builtin_amdgcn_s_setprio(1); _Pragma("unroll") for (int m = 0; m < 4; ++m) _Pragma("unroll") for (int n = 0; n < 2; ++n) _Pragma("unroll") for (int k = 0; k < 2; ++k) \
;         acc[ai][bj][m][n] = __builtin_amdgcn_mfma_f32_16x16x32_bf16(Bt[n][k], At[m][k], acc[ai][bj][m][n], 0, 0, 0); __builtin_amdgcn_s_setprio(0); } while (0)
; #define PG8_WAIT_V(n) asm volatile("s_waitcnt vmcnt(" #n ")" ::: "memory")
; #define PG8_WAIT_L(n) asm volatile("s_waitcnt lgkmcnt(" #n ")" ::: "memory")
; template <class Epi, class Sched, bool ALIGN_EPI = false, bool SP2 = false>
; __device__ __forceinline__ void gemm_phase(LAS unsigned char* lds, const Gemm g, const Sched& S, const Epi& E, const int tid) {
;     ...
;         const char* nA = has_next ? (const char*)g.A + (size_t)nxt.pm * tstep : cA; const char* nB = has_next ? (const char*)g.Bt + (size_t)nxt.pn * tstep : cB;
;         for (int t = 0; t < nt; t += 2) {
;             const bool last = (t == nt - 2);
;             const char* a1 = cA + (size_t)(t + 1) * kstep;
;             const char* a2 = last ? nA : cA + (size_t)(t + 2) * kstep; const char* b2 = last ? nB : cB + (size_t)(t + 2) * kstep;
;             const char* a3 = a2 + kstep; const char* b3 = b2 + kstep;
;             if constexpr (SP2) {
;             PG8_LDB(B0, 0, 0); PG8_LDB(B1, 0, 1); PG8_SCHED; PG8_LDA(At, 0, 0); PG8_STAGE(PG8_SA(1, 1), a1 + hstep, voffA);
;             PG8_WAIT_V(8); PG8_WAIT_L(0); PG8_BAR; PG8_MMA(0, 0, At, B0); PG8_MMA(0, 1, At, B1); PG8_BAR; PG8_SCHED;
;             PG8_LDA(At, 0, 1); PG8_STAGE(PG8_SB(0, 0), b2, voffB); PG8_STAGE(PG8_SB(0, 1), b2 + hstep, voffB); PG8_STAGE(PG8_SA(0, 0), a2, voffA);
.LBB0_1411:
	s_add_u32 s22, s20, 0xfff80080
	s_addc_u32 s23, s21, -1
	s_add_i32 s49, 0, 0x10000
	s_cmp_eq_u32 s48, 28
	s_cselect_b32 s25, s1, s23
	s_cselect_b32 s24, s5, s22
	v_add_u32_e32 v140, s49, v142
	s_cselect_b32 s23, s13, s47
	s_cselect_b32 s22, s15, s46
	s_add_i32 s52, 0, 0x14000
	ds_read_b128 v[136:139], v140
	ds_read_b128 v[154:157], v140 offset:1024
	ds_read_b128 v[158:161], v140 offset:2048
	ds_read_b128 v[162:165], v140 offset:3072
	v_add_u32_e32 v140, s52, v142
	ds_read_b128 v[188:191], v140
	ds_read_b128 v[192:195], v140 offset:1024
	ds_read_b128 v[196:199], v140 offset:2048
	ds_read_b128 v[200:203], v140 offset:3072
	v_lshl_add_u64 v[150:151], s[20:21], 0, v[132:133]
	s_add_i32 m0, s37, 0xc000
	ds_read_b128 v[204:207], v152
	ds_read_b128 v[208:211], v152 offset:1024
	ds_read_b128 v[212:215], v152 offset:2048
	ds_read_b128 v[216:219], v152 offset:3072
	ds_read_b128 v[220:223], v152 offset:4096
	ds_read_b128 v[228:231], v152 offset:5120
	ds_read_b128 v[232:235], v152 offset:6144
	ds_read_b128 v[236:239], v152 offset:7168
	global_load_lds_dwordx4 v[150:151], off
	v_lshl_add_u64 v[150:151], s[20:21], 0, v[134:135]
	s_add_i32 m0, s37, 0xe000
	s_nop 0
	global_load_lds_dwordx4 v[150:151], off
	s_waitcnt vmcnt(8)
	s_waitcnt lgkmcnt(0)
	s_barrier
	s_setprio 1
	s_waitcnt lgkmcnt(0)
	v_mfma_f32_16x16x32_bf16 v[124:127], v[136:139], v[204:207], v[124:127]
	v_mfma_f32_16x16x32_bf16 v[120:123], v[158:161], v[204:207], v[120:123]
	v_mfma_f32_16x16x32_bf16 v[108:111], v[136:139], v[212:215], v[108:111]
	v_mfma_f32_16x16x32_bf16 v[104:107], v[158:161], v[212:215], v[104:107]
	v_mfma_f32_16x16x32_bf16 v[92:95], v[136:139], v[220:223], v[92:95]
	v_mfma_f32_16x16x32_bf16 v[88:91], v[158:161], v[220:223], v[88:91]
	v_mfma_f32_16x16x32_bf16 v[76:79], v[136:139], v[232:235], v[76:79]
	v_mfma_f32_16x16x32_bf16 v[72:75], v[158:161], v[232:235], v[72:75]
	v_mfma_f32_16x16x32_bf16 v[124:127], v[154:157], v[208:211], v[124:127]
	v_mfma_f32_16x16x32_bf16 v[120:123], v[162:165], v[208:211], v[120:123]
	v_mfma_f32_16x16x32_bf16 v[108:111], v[154:157], v[216:219], v[108:111]
	v_mfma_f32_16x16x32_bf16 v[104:107], v[162:165], v[216:219], v[104:107]
	v_mfma_f32_16x16x32_bf16 v[92:95], v[154:157], v[228:231], v[92:95]
	v_mfma_f32_16x16x32_bf16 v[88:91], v[162:165], v[228:231], v[88:91]
	v_mfma_f32_16x16x32_bf16 v[76:79], v[154:157], v[236:239], v[76:79]
	v_mfma_f32_16x16x32_bf16 v[72:75], v[162:165], v[236:239], v[72:75]
	s_setprio 0
	s_setprio 1
	v_mfma_f32_16x16x32_bf16 v[116:119], v[188:191], v[204:207], v[116:119]
	v_mfma_f32_16x16x32_bf16 v[112:115], v[196:199], v[204:207], v[112:115]
	v_mfma_f32_16x16x32_bf16 v[100:103], v[188:191], v[212:215], v[100:103]
	v_mfma_f32_16x16x32_bf16 v[96:99], v[196:199], v[212:215], v[96:99]
	v_mfma_f32_16x16x32_bf16 v[84:87], v[188:191], v[220:223], v[84:87]
	v_mfma_f32_16x16x32_bf16 v[80:83], v[196:199], v[220:223], v[80:83]
	v_mfma_f32_16x16x32_bf16 v[68:71], v[188:191], v[232:235], v[68:71]
	v_mfma_f32_16x16x32_bf16 v[64:67], v[196:199], v[232:235], v[64:67]
	v_mfma_f32_16x16x32_bf16 v[116:119], v[192:195], v[208:211], v[116:119]
	v_mfma_f32_16x16x32_bf16 v[112:115], v[200:203], v[208:211], v[112:115]
	v_mfma_f32_16x16x32_bf16 v[100:103], v[192:195], v[216:219], v[100:103]
	v_mfma_f32_16x16x32_bf16 v[96:99], v[200:203], v[216:219], v[96:99]
	v_mfma_f32_16x16x32_bf16 v[84:87], v[192:195], v[228:231], v[84:87]
	v_mfma_f32_16x16x32_bf16 v[80:83], v[200:203], v[228:231], v[80:83]
	v_mfma_f32_16x16x32_bf16 v[68:71], v[192:195], v[236:239], v[68:71]
	v_mfma_f32_16x16x32_bf16 v[64:67], v[200:203], v[236:239], v[64:67]
	s_setprio 0
	s_barrier
	s_add_i32 s49, s49, s30
	v_lshl_add_u64 v[150:151], s[22:23], 0, v[144:145]
	s_mov_b32 m0, s49
	ds_read_b128 v[204:207], v152 offset:16384
	ds_read_b128 v[208:211], v152 offset:17408
	ds_read_b128 v[212:215], v152 offset:18432
	ds_read_b128 v[216:219], v152 offset:19456
	ds_read_b128 v[220:223], v152 offset:20480
	ds_read_b128 v[228:231], v152 offset:21504
	ds_read_b128 v[232:235], v152 offset:22528
	ds_read_b128 v[236:239], v152 offset:23552
	global_load_lds_dwordx4 v[150:151], off
	s_add_i32 m0, s49, 0x2000
	s_add_u32 s50, s22, 0x80000
	v_lshl_add_u64 v[240:241], s[22:23], 0, v[128:129]
	s_addc_u32 s51, s23, 0
	s_add_i32 s49, s52, s30
	global_load_lds_dwordx4 v[240:241], off
	v_lshl_add_u64 v[242:243], s[50:51], 0, v[144:145]
	s_mov_b32 m0, s49
	v_lshl_add_u64 v[244:245], s[24:25], 0, v[128:129]
	global_load_lds_dwordx4 v[242:243], off
	v_lshl_add_u64 v[242:243], s[50:51], 0, v[128:129]
	s_add_i32 m0, s49, 0x2000
	s_nop 0
	global_load_lds_dwordx4 v[242:243], off
	v_lshl_add_u64 v[242:243], s[24:25], 0, v[144:145]
	s_mov_b32 m0, s37
	s_nop 0
	global_load_lds_dwordx4 v[242:243], off
	s_mov_b32 m0, s38
	s_nop 0
	global_load_lds_dwordx4 v[244:245], off
	s_waitcnt vmcnt(8)
	s_waitcnt lgkmcnt(0)
	s_barrier
; #define PG8_STAGE(bufoff, gbase, voff) do { _Pragma("unroll") for (int _i = 0; _i < 2; ++_i) \
;         __builtin_amdgcn_global_load_lds((const unsigned*)((const char*)(gbase) + (voff)[_i]), (LAS unsigned*)(lds + (bufoff) + ldsw + _i * 8192), 16, 0, 0); } while (0)
; #define PG8_LDA(dst, b, h) do { _Pragma("unroll") for (int m = 0; m < 4; ++m) _Pragma("unroll") for (int k = 0; k < 2; ++k) dst[m][k] = *(const LAS bf16x8*)(lds + PG8_SA(b, h) + aoff + m * 2048 + k * 1024); } while (0)
; #define PG8_LDB(dst, b, h) do { _Pragma("unroll") for (int n = 0; n < 2; ++n) _Pragma("unroll") for (int k = 0; k < 2; ++k) dst[n][k] = *(const LAS bf16x8*)(lds + PG8_SB(b, h) + boff + n * 2048 + k * 1024); } while (0)
; #define PG8_MMA(ai, bj, At, Bt) do { __builtin_amdgcn_s_setprio(1); _Pragma("unroll") for (int m = 0; m < 4; ++m) _Pragma("unroll") for (int n = 0; n < 2; ++n) _Pragma("unroll") for (int k = 0; k < 2; ++k) \
;         acc[ai][bj][m][n] = __builtin_amdgcn_mfma_f32_16x16x32_bf16(Bt[n][k], At[m][k], acc[ai][bj][m][n], 0, 0, 0); __builtin_amdgcn_s_setprio(0); } while (0)
; #define PG8_WAIT_V(n) asm volatile("s_waitcnt vmcnt(" #n ")" ::: "memory")
; #define PG8_WAIT_L(n) asm volatile("s_waitcnt lgkmcnt(" #n ")" ::: "memory")
; #define PG8_BAR __builtin_amdgcn_s_barrier()
; #define PG8_SCHED __builtin_amdgcn_sched_barrier(0)
; template <class Epi, class Sched, bool ALIGN_EPI = false, bool SP2 = false>
; __device__ __forceinline__ void gemm_phase(LAS unsigned char* lds, const Gemm g, const Sched& S, const Epi& E, const int tid) {
;     ...
;             PG8_WAIT_V(8); PG8_WAIT_L(0); PG8_BAR; PG8_MMA(1, 0, At, B0); PG8_MMA(1, 1, At, B1); PG8_BAR; PG8_SCHED;
;             PG8_LDB(B0, 1, 0); PG8_LDB(B1, 1, 1); PG8_SCHED; PG8_LDA(At, 1, 0); PG8_STAGE(PG8_SA(0, 1), a2 + hstep, voffA);
;             PG8_WAIT_V(8); PG8_WAIT_L(0); PG8_BAR; PG8_MMA(0, 0, At, B0); PG8_MMA(0, 1, At, B1); PG8_BAR; PG8_SCHED;
	s_setprio 1
	s_waitcnt lgkmcnt(0)
	v_mfma_f32_16x16x32_bf16 v[60:63], v[136:139], v[204:207], v[60:63]
	v_mfma_f32_16x16x32_bf16 v[56:59], v[158:161], v[204:207], v[56:59]
	v_mfma_f32_16x16x32_bf16 v[44:47], v[136:139], v[212:215], v[44:47]
	v_mfma_f32_16x16x32_bf16 v[40:43], v[158:161], v[212:215], v[40:43]
	v_mfma_f32_16x16x32_bf16 v[28:31], v[136:139], v[220:223], v[28:31]
	v_mfma_f32_16x16x32_bf16 v[24:27], v[158:161], v[220:223], v[24:27]
	v_mfma_f32_16x16x32_bf16 v[12:15], v[136:139], v[232:235], v[12:15]
	v_mfma_f32_16x16x32_bf16 v[8:11], v[158:161], v[232:235], v[8:11]
	v_mfma_f32_16x16x32_bf16 v[60:63], v[154:157], v[208:211], v[60:63]
	v_mfma_f32_16x16x32_bf16 v[56:59], v[162:165], v[208:211], v[56:59]
	v_mfma_f32_16x16x32_bf16 v[44:47], v[154:157], v[216:219], v[44:47]
	v_mfma_f32_16x16x32_bf16 v[40:43], v[162:165], v[216:219], v[40:43]
	v_mfma_f32_16x16x32_bf16 v[28:31], v[154:157], v[228:231], v[28:31]
	v_mfma_f32_16x16x32_bf16 v[24:27], v[162:165], v[228:231], v[24:27]
	v_mfma_f32_16x16x32_bf16 v[12:15], v[154:157], v[236:239], v[12:15]
	v_mfma_f32_16x16x32_bf16 v[8:11], v[162:165], v[236:239], v[8:11]
	s_setprio 0
	s_setprio 1
	v_mfma_f32_16x16x32_bf16 v[52:55], v[188:191], v[204:207], v[52:55]
	v_mfma_f32_16x16x32_bf16 v[48:51], v[196:199], v[204:207], v[48:51]
	v_mfma_f32_16x16x32_bf16 v[36:39], v[188:191], v[212:215], v[36:39]
	v_mfma_f32_16x16x32_bf16 v[32:35], v[196:199], v[212:215], v[32:35]
	v_mfma_f32_16x16x32_bf16 v[20:23], v[188:191], v[220:223], v[20:23]
	v_mfma_f32_16x16x32_bf16 v[16:19], v[196:199], v[220:223], v[16:19]
	v_mfma_f32_16x16x32_bf16 v[4:7], v[188:191], v[232:235], v[4:7]
	v_mfma_f32_16x16x32_bf16 v[0:3], v[196:199], v[232:235], v[0:3]
	v_mfma_f32_16x16x32_bf16 v[52:55], v[192:195], v[208:211], v[52:55]
	v_mfma_f32_16x16x32_bf16 v[48:51], v[200:203], v[208:211], v[48:51]
	v_mfma_f32_16x16x32_bf16 v[36:39], v[192:195], v[216:219], v[36:39]
	v_mfma_f32_16x16x32_bf16 v[32:35], v[200:203], v[216:219], v[32:35]
	v_mfma_f32_16x16x32_bf16 v[20:23], v[192:195], v[228:231], v[20:23]
	v_mfma_f32_16x16x32_bf16 v[16:19], v[200:203], v[228:231], v[16:19]
	v_mfma_f32_16x16x32_bf16 v[4:7], v[192:195], v[236:239], v[4:7]
	v_mfma_f32_16x16x32_bf16 v[0:3], v[200:203], v[236:239], v[0:3]
	s_setprio 0
	s_barrier
	s_add_i32 s49, 0, 0x18000
	v_add_u32_e32 v140, s49, v142
	s_add_i32 s50, 0, 0x1c000
	ds_read_b128 v[136:139], v140
	ds_read_b128 v[154:157], v140 offset:1024
	ds_read_b128 v[158:161], v140 offset:2048
	ds_read_b128 v[162:165], v140 offset:3072
	v_add_u32_e32 v140, s50, v142
	ds_read_b128 v[188:191], v140
	ds_read_b128 v[192:195], v140 offset:1024
	ds_read_b128 v[196:199], v140 offset:2048
	ds_read_b128 v[200:203], v140 offset:3072
	s_add_u32 s24, s24, 0x80000
	s_addc_u32 s25, s25, 0
	s_mov_b32 m0, s39
	v_lshl_add_u64 v[246:247], s[24:25], 0, v[144:145]
	ds_read_b128 v[204:207], v152 offset:32768
	ds_read_b128 v[208:211], v152 offset:33792
	ds_read_b128 v[212:215], v152 offset:34816
	ds_read_b128 v[216:219], v152 offset:35840
	ds_read_b128 v[220:223], v152 offset:36864
	ds_read_b128 v[228:231], v152 offset:37888
	ds_read_b128 v[232:235], v152 offset:38912
	ds_read_b128 v[236:239], v152 offset:39936
	global_load_lds_dwordx4 v[246:247], off
	v_lshl_add_u64 v[246:247], s[24:25], 0, v[128:129]
	s_mov_b32 m0, s40
	s_nop 0
	global_load_lds_dwordx4 v[246:247], off
	s_waitcnt vmcnt(8)
	s_waitcnt lgkmcnt(0)
	s_barrier
	s_setprio 1
	s_waitcnt lgkmcnt(0)
	v_mfma_f32_16x16x32_bf16 v[124:127], v[136:139], v[204:207], v[124:127]
	v_mfma_f32_16x16x32_bf16 v[120:123], v[158:161], v[204:207], v[120:123]
	v_mfma_f32_16x16x32_bf16 v[108:111], v[136:139], v[212:215], v[108:111]
	v_mfma_f32_16x16x32_bf16 v[104:107], v[158:161], v[212:215], v[104:107]
	v_mfma_f32_16x16x32_bf16 v[92:95], v[136:139], v[220:223], v[92:95]
	v_mfma_f32_16x16x32_bf16 v[88:91], v[158:161], v[220:223], v[88:91]
	v_mfma_f32_16x16x32_bf16 v[76:79], v[136:139], v[232:235], v[76:79]
	v_mfma_f32_16x16x32_bf16 v[72:75], v[158:161], v[232:235], v[72:75]
	v_mfma_f32_16x16x32_bf16 v[124:127], v[154:157], v[208:211], v[124:127]
	v_mfma_f32_16x16x32_bf16 v[120:123], v[162:165], v[208:211], v[120:123]
	v_mfma_f32_16x16x32_bf16 v[108:111], v[154:157], v[216:219], v[108:111]
	v_mfma_f32_16x16x32_bf16 v[104:107], v[162:165], v[216:219], v[104:107]
	v_mfma_f32_16x16x32_bf16 v[92:95], v[154:157], v[228:231], v[92:95]
	v_mfma_f32_16x16x32_bf16 v[88:91], v[162:165], v[228:231], v[88:91]
	v_mfma_f32_16x16x32_bf16 v[76:79], v[154:157], v[236:239], v[76:79]
	v_mfma_f32_16x16x32_bf16 v[72:75], v[162:165], v[236:239], v[72:75]
	s_setprio 0
	s_setprio 1
	v_mfma_f32_16x16x32_bf16 v[116:119], v[188:191], v[204:207], v[116:119]
	v_mfma_f32_16x16x32_bf16 v[112:115], v[196:199], v[204:207], v[112:115]
	v_mfma_f32_16x16x32_bf16 v[100:103], v[188:191], v[212:215], v[100:103]
	v_mfma_f32_16x16x32_bf16 v[96:99], v[196:199], v[212:215], v[96:99]
	v_mfma_f32_16x16x32_bf16 v[84:87], v[188:191], v[220:223], v[84:87]
	v_mfma_f32_16x16x32_bf16 v[80:83], v[196:199], v[220:223], v[80:83]
	v_mfma_f32_16x16x32_bf16 v[68:71], v[188:191], v[232:235], v[68:71]
	v_mfma_f32_16x16x32_bf16 v[64:67], v[196:199], v[232:235], v[64:67]
	v_mfma_f32_16x16x32_bf16 v[116:119], v[192:195], v[208:211], v[116:119]
	v_mfma_f32_16x16x32_bf16 v[112:115], v[200:203], v[208:211], v[112:115]
	v_mfma_f32_16x16x32_bf16 v[100:103], v[192:195], v[216:219], v[100:103]
	v_mfma_f32_16x16x32_bf16 v[96:99], v[200:203], v[216:219], v[96:99]
	v_mfma_f32_16x16x32_bf16 v[84:87], v[192:195], v[228:231], v[84:87]
	v_mfma_f32_16x16x32_bf16 v[80:83], v[200:203], v[228:231], v[80:83]
	v_mfma_f32_16x16x32_bf16 v[68:71], v[192:195], v[236:239], v[68:71]
	v_mfma_f32_16x16x32_bf16 v[64:67], v[200:203], v[236:239], v[64:67]
	s_setprio 0
	s_barrier
; #define PG8_STAGE(bufoff, gbase, voff) do { _Pragma("unroll") for (int _i = 0; _i < 2; ++_i) \
;         __builtin_amdgcn_global_load_lds((const unsigned*)((const char*)(gbase) + (voff)[_i]), (LAS unsigned*)(lds + (bufoff) + ldsw + _i * 8192), 16, 0, 0); } while (0)
; #define PG8_LDA(dst, b, h) do { _Pragma("unroll") for (int m = 0; m < 4; ++m) _Pragma("unroll") for (int k = 0; k < 2; ++k) dst[m][k] = *(const LAS bf16x8*)(lds + PG8_SA(b, h) + aoff + m * 2048 + k * 1024); } while (0)
; #define PG8_MMA(ai, bj, At, Bt) do { __builtin_amdgcn_s_setprio(1); _Pragma("unroll") for (int m = 0; m < 4; ++m) _Pragma("unroll") for (int n = 0; n < 2; ++n) _Pragma("unroll") for (int k = 0; k < 2; ++k) \
;         acc[ai][bj][m][n] = __builtin_amdgcn_mfma_f32_16x16x32_bf16(Bt[n][k], At[m][k], acc[ai][bj][m][n], 0, 0, 0); __builtin_amdgcn_s_setprio(0); } while (0)
; #define PG8_WAIT_V(n) asm volatile("s_waitcnt vmcnt(" #n ")" ::: "memory")
; #define PG8_WAIT_L(n) asm volatile("s_waitcnt lgkmcnt(" #n ")" ::: "memory")
; #define PG8_BAR __builtin_amdgcn_s_barrier()
; #define PG8_SCHED __builtin_amdgcn_sched_barrier(0)
; template <class Epi, class Sched, bool ALIGN_EPI = false, bool SP2 = false>
; __device__ __forceinline__ void gemm_phase(LAS unsigned char* lds, const Gemm g, const Sched& S, const Epi& E, const int tid) {
;     ...
;         for (int t = 0; t < nt; t += 2) {
;             const bool last = (t == nt - 2);
;             const char* a1 = cA + (size_t)(t + 1) * kstep;
;             const char* a2 = last ? nA : cA + (size_t)(t + 2) * kstep; const char* b2 = last ? nB : cB + (size_t)(t + 2) * kstep;
;             const char* a3 = a2 + kstep; const char* b3 = b2 + kstep;
;     ...
;             PG8_LDA(At, 1, 1); PG8_STAGE(PG8_SB(1, 0), b3, voffB); PG8_STAGE(PG8_SB(1, 1), b3 + hstep, voffB); PG8_STAGE(PG8_SA(1, 0), a3, voffA);
;             PG8_WAIT_V(8); PG8_WAIT_L(0); PG8_BAR; PG8_MMA(1, 0, At, B0); PG8_MMA(1, 1, At, B1); PG8_BAR; PG8_SCHED;
	s_add_i32 s24, s49, s30
	v_lshl_add_u64 v[150:151], v[150:151], 0, s[70:71]
	s_mov_b32 m0, s24
	ds_read_b128 v[204:207], v152 offset:49152
	ds_read_b128 v[208:211], v152 offset:50176
	ds_read_b128 v[212:215], v152 offset:51200
	ds_read_b128 v[216:219], v152 offset:52224
	ds_read_b128 v[220:223], v152 offset:53248
	ds_read_b128 v[228:231], v152 offset:54272
	ds_read_b128 v[232:235], v152 offset:55296
	ds_read_b128 v[236:239], v152 offset:56320
	global_load_lds_dwordx4 v[150:151], off
	s_add_i32 m0, s24, 0x2000
	s_add_u32 s22, s22, 0x80080
	v_lshl_add_u64 v[150:151], v[240:241], 0, s[70:71]
	s_addc_u32 s23, s23, 0
	s_add_i32 s24, s50, s30
	global_load_lds_dwordx4 v[150:151], off
	v_lshl_add_u64 v[150:151], s[22:23], 0, v[144:145]
	s_mov_b32 m0, s24
	s_nop 0
	global_load_lds_dwordx4 v[150:151], off
	v_lshl_add_u64 v[150:151], s[22:23], 0, v[128:129]
	s_add_i32 m0, s24, 0x2000
	s_nop 0
	global_load_lds_dwordx4 v[150:151], off
	v_lshl_add_u64 v[150:151], v[242:243], 0, s[70:71]
	s_mov_b32 m0, s42
	s_nop 0
	global_load_lds_dwordx4 v[150:151], off
	v_lshl_add_u64 v[150:151], v[244:245], 0, s[70:71]
	s_mov_b32 m0, s43
	s_nop 0
	global_load_lds_dwordx4 v[150:151], off
	s_waitcnt vmcnt(8)
	s_waitcnt lgkmcnt(0)
	s_barrier
	s_setprio 1
	s_waitcnt lgkmcnt(0)
	v_mfma_f32_16x16x32_bf16 v[60:63], v[136:139], v[204:207], v[60:63]
	v_mfma_f32_16x16x32_bf16 v[56:59], v[158:161], v[204:207], v[56:59]
	v_mfma_f32_16x16x32_bf16 v[44:47], v[136:139], v[212:215], v[44:47]
	v_mfma_f32_16x16x32_bf16 v[40:43], v[158:161], v[212:215], v[40:43]
	v_mfma_f32_16x16x32_bf16 v[28:31], v[136:139], v[220:223], v[28:31]
	v_mfma_f32_16x16x32_bf16 v[24:27], v[158:161], v[220:223], v[24:27]
	v_mfma_f32_16x16x32_bf16 v[12:15], v[136:139], v[232:235], v[12:15]
	v_mfma_f32_16x16x32_bf16 v[8:11], v[158:161], v[232:235], v[8:11]
	v_mfma_f32_16x16x32_bf16 v[60:63], v[154:157], v[208:211], v[60:63]
	v_mfma_f32_16x16x32_bf16 v[56:59], v[162:165], v[208:211], v[56:59]
	v_mfma_f32_16x16x32_bf16 v[44:47], v[154:157], v[216:219], v[44:47]
	v_mfma_f32_16x16x32_bf16 v[40:43], v[162:165], v[216:219], v[40:43]
	v_mfma_f32_16x16x32_bf16 v[28:31], v[154:157], v[228:231], v[28:31]
	v_mfma_f32_16x16x32_bf16 v[24:27], v[162:165], v[228:231], v[24:27]
	v_mfma_f32_16x16x32_bf16 v[12:15], v[154:157], v[236:239], v[12:15]
	v_mfma_f32_16x16x32_bf16 v[8:11], v[162:165], v[236:239], v[8:11]
	s_setprio 0
	s_setprio 1
	v_mfma_f32_16x16x32_bf16 v[52:55], v[188:191], v[204:207], v[52:55]
	v_mfma_f32_16x16x32_bf16 v[48:51], v[196:199], v[204:207], v[48:51]
	v_mfma_f32_16x16x32_bf16 v[36:39], v[188:191], v[212:215], v[36:39]
	v_mfma_f32_16x16x32_bf16 v[32:35], v[196:199], v[212:215], v[32:35]
	v_mfma_f32_16x16x32_bf16 v[20:23], v[188:191], v[220:223], v[20:23]
	v_mfma_f32_16x16x32_bf16 v[16:19], v[196:199], v[220:223], v[16:19]
	v_mfma_f32_16x16x32_bf16 v[4:7], v[188:191], v[232:235], v[4:7]
	v_mfma_f32_16x16x32_bf16 v[0:3], v[196:199], v[232:235], v[0:3]
	v_mfma_f32_16x16x32_bf16 v[52:55], v[192:195], v[208:211], v[52:55]
	v_mfma_f32_16x16x32_bf16 v[48:51], v[200:203], v[208:211], v[48:51]
	v_mfma_f32_16x16x32_bf16 v[36:39], v[192:195], v[216:219], v[36:39]
	v_mfma_f32_16x16x32_bf16 v[32:35], v[200:203], v[216:219], v[32:35]
	v_mfma_f32_16x16x32_bf16 v[20:23], v[192:195], v[228:231], v[20:23]
	v_mfma_f32_16x16x32_bf16 v[16:19], v[200:203], v[228:231], v[16:19]
	v_mfma_f32_16x16x32_bf16 v[4:7], v[192:195], v[236:239], v[4:7]
	v_mfma_f32_16x16x32_bf16 v[0:3], v[200:203], v[236:239], v[0:3]
	s_setprio 0
	s_add_i32 s48, s48, 2
	s_add_u32 s20, s20, 0x100
	s_addc_u32 s21, s21, 0
	s_add_u32 s46, s46, 0x100
	s_addc_u32 s47, s47, 0
	s_cmp_gt_u32 s48, 29
	s_barrier
	s_cbranch_scc0 .LBB0_1411
	s_and_b64 vcc, exec, s[10:11]
	s_cbranch_vccz .LBB0_1414
	s_barrier

; #define PG8_STAGE(bufoff, gbase, voff) do { _Pragma("unroll") for (int _i = 0; _i < 2; ++_i) \
;         __builtin_amdgcn_global_load_lds((const unsigned*)((const char*)(gbase) + (voff)[_i]), (LAS unsigned*)(lds + (bufoff) + ldsw + _i * 8192), 16, 0, 0); } while (0)
; #define PG8_LDA(dst, b, h) do { _Pragma("unroll") for (int m = 0; m < 4; ++m) _Pragma("unroll") for (int k = 0; k < 2; ++k) dst[m][k] = *(const LAS bf16x8*)(lds + PG8_SA(b, h) + aoff + m * 2048 + k * 1024); } while (0)
; #define PG8_LDB(dst, b, h) do { _Pragma("unroll") for (int n = 0; n < 2; ++n) _Pragma("unroll") for (int k = 0; k < 2; ++k) dst[n][k] = *(const LAS bf16x8*)(lds + PG8_SB(b, h) + boff + n * 2048 + k * 1024); } while (0)
; #define PG8_MMA(ai, bj, At, Bt) do { __builtin_amdgcn_s_setprio(1); _Pragma("unroll") for (int m = 0; m < 4; ++m) _Pragma("unroll") for (int n = 0; n < 2; ++n) _Pragma("unroll") for (int k = 0; k < 2; ++k) \
;         acc[ai][bj][m][n] = __builtin_amdgcn_mfma_f32_16x16x32_bf16(Bt[n][k], At[m][k], acc[ai][bj][m][n], 0, 0, 0); __builtin_amdgcn_s_setprio(0); } while (0)
; #define PG8_WAIT_V(n) asm volatile("s_waitcnt vmcnt(" #n ")" ::: "memory")
; #define PG8_WAIT_L(n) asm volatile("s_waitcnt lgkmcnt(" #n ")" ::: "memory")
; template <class Epi, class Sched, bool ALIGN_EPI = false, bool SP2 = false>
; __device__ __forceinline__ void gemm_phase(LAS unsigned char* lds, const Gemm g, const Sched& S, const Epi& E, const int tid) {
;     ...
;         const char* nA = has_next ? (const char*)g.A + (size_t)nxt.pm * tstep : cA; const char* nB = has_next ? (const char*)g.Bt + (size_t)nxt.pn * tstep : cB;
;         for (int t = 0; t < nt; t += 2) {
;             const bool last = (t == nt - 2);
;             const char* a1 = cA + (size_t)(t + 1) * kstep;
;             const char* a2 = last ? nA : cA + (size_t)(t + 2) * kstep; const char* b2 = last ? nB : cB + (size_t)(t + 2) * kstep;
;             const char* a3 = a2 + kstep; const char* b3 = b2 + kstep;
;             if constexpr (SP2) {
;             PG8_LDB(B0, 0, 0); PG8_LDB(B1, 0, 1); PG8_SCHED; PG8_LDA(At, 0, 0); PG8_STAGE(PG8_SA(1, 1), a1 + hstep, voffA);
;             PG8_WAIT_V(8); PG8_WAIT_L(0); PG8_BAR; PG8_MMA(0, 0, At, B0); PG8_MMA(0, 1, At, B1); PG8_BAR; PG8_SCHED;
;             PG8_LDA(At, 0, 1); PG8_STAGE(PG8_SB(0, 0), b2, voffB); PG8_STAGE(PG8_SB(0, 1), b2 + hstep, voffB); PG8_STAGE(PG8_SA(0, 0), a2, voffA);
.LBB0_1487:
	s_add_u32 s16, s0, 0x100
	s_addc_u32 s17, s1, 0
	s_add_i32 s50, 0, 0x10000
	s_cmpk_eq_i32 s49, 0x54
	s_cselect_b32 s21, s7, s17
	s_cselect_b32 s20, s6, s16
	v_add_u32_e32 v138, s50, v141
	s_cselect_b32 s19, s15, s48
	s_cselect_b32 s18, s14, s47
	s_add_i32 s51, 0, 0x14000
	ds_read_b128 v[134:137], v138
	ds_read_b128 v[152:155], v138 offset:1024
	ds_read_b128 v[156:159], v138 offset:2048
	ds_read_b128 v[160:163], v138 offset:3072
	v_add_u32_e32 v138, s51, v141
	ds_read_b128 v[188:191], v138
	ds_read_b128 v[192:195], v138 offset:1024
	ds_read_b128 v[196:199], v138 offset:2048
	ds_read_b128 v[200:203], v138 offset:3072
	v_lshl_add_u64 v[138:139], s[0:1], 0, v[130:131]
	s_add_i32 m0, s29, 0xc000
	ds_read_b128 v[204:207], v143
	ds_read_b128 v[208:211], v143 offset:1024
	ds_read_b128 v[212:215], v143 offset:2048
	ds_read_b128 v[216:219], v143 offset:3072
	ds_read_b128 v[220:223], v143 offset:4096
	ds_read_b128 v[228:231], v143 offset:5120
	ds_read_b128 v[232:235], v143 offset:6144
	ds_read_b128 v[236:239], v143 offset:7168
	global_load_lds_dwordx4 v[138:139], off
	v_lshl_add_u64 v[138:139], s[0:1], 0, v[132:133]
	s_add_i32 m0, s29, 0xe000
	s_nop 0
	global_load_lds_dwordx4 v[138:139], off
	s_waitcnt vmcnt(8)
	s_waitcnt lgkmcnt(0)
	s_barrier
	s_setprio 1
	s_waitcnt lgkmcnt(0)
	v_mfma_f32_16x16x32_bf16 v[124:127], v[134:137], v[204:207], v[124:127]
	v_mfma_f32_16x16x32_bf16 v[120:123], v[156:159], v[204:207], v[120:123]
	v_mfma_f32_16x16x32_bf16 v[108:111], v[134:137], v[212:215], v[108:111]
	v_mfma_f32_16x16x32_bf16 v[104:107], v[156:159], v[212:215], v[104:107]
	v_mfma_f32_16x16x32_bf16 v[92:95], v[134:137], v[220:223], v[92:95]
	v_mfma_f32_16x16x32_bf16 v[88:91], v[156:159], v[220:223], v[88:91]
	v_mfma_f32_16x16x32_bf16 v[76:79], v[134:137], v[232:235], v[76:79]
	v_mfma_f32_16x16x32_bf16 v[72:75], v[156:159], v[232:235], v[72:75]
	v_mfma_f32_16x16x32_bf16 v[124:127], v[152:155], v[208:211], v[124:127]
	v_mfma_f32_16x16x32_bf16 v[120:123], v[160:163], v[208:211], v[120:123]
	v_mfma_f32_16x16x32_bf16 v[108:111], v[152:155], v[216:219], v[108:111]
	v_mfma_f32_16x16x32_bf16 v[104:107], v[160:163], v[216:219], v[104:107]
	v_mfma_f32_16x16x32_bf16 v[92:95], v[152:155], v[228:231], v[92:95]
	v_mfma_f32_16x16x32_bf16 v[88:91], v[160:163], v[228:231], v[88:91]
	v_mfma_f32_16x16x32_bf16 v[76:79], v[152:155], v[236:239], v[76:79]
	v_mfma_f32_16x16x32_bf16 v[72:75], v[160:163], v[236:239], v[72:75]
	s_setprio 0
	s_setprio 1
	v_mfma_f32_16x16x32_bf16 v[116:119], v[188:191], v[204:207], v[116:119]
	v_mfma_f32_16x16x32_bf16 v[112:115], v[196:199], v[204:207], v[112:115]
	v_mfma_f32_16x16x32_bf16 v[100:103], v[188:191], v[212:215], v[100:103]
	v_mfma_f32_16x16x32_bf16 v[96:99], v[196:199], v[212:215], v[96:99]
	v_mfma_f32_16x16x32_bf16 v[84:87], v[188:191], v[220:223], v[84:87]
	v_mfma_f32_16x16x32_bf16 v[80:83], v[196:199], v[220:223], v[80:83]
	v_mfma_f32_16x16x32_bf16 v[68:71], v[188:191], v[232:235], v[68:71]
	v_mfma_f32_16x16x32_bf16 v[64:67], v[196:199], v[232:235], v[64:67]
	v_mfma_f32_16x16x32_bf16 v[116:119], v[192:195], v[208:211], v[116:119]
	v_mfma_f32_16x16x32_bf16 v[112:115], v[200:203], v[208:211], v[112:115]
	v_mfma_f32_16x16x32_bf16 v[100:103], v[192:195], v[216:219], v[100:103]
	v_mfma_f32_16x16x32_bf16 v[96:99], v[200:203], v[216:219], v[96:99]
	v_mfma_f32_16x16x32_bf16 v[84:87], v[192:195], v[228:231], v[84:87]
	v_mfma_f32_16x16x32_bf16 v[80:83], v[200:203], v[228:231], v[80:83]
	v_mfma_f32_16x16x32_bf16 v[68:71], v[192:195], v[236:239], v[68:71]
	v_mfma_f32_16x16x32_bf16 v[64:67], v[200:203], v[236:239], v[64:67]
	s_setprio 0
	s_barrier
	s_add_i32 s0, s50, s28
	v_lshl_add_u64 v[138:139], s[18:19], 0, v[144:145]
	s_mov_b32 m0, s0
	ds_read_b128 v[204:207], v143 offset:16384
	ds_read_b128 v[208:211], v143 offset:17408
	ds_read_b128 v[212:215], v143 offset:18432
	ds_read_b128 v[216:219], v143 offset:19456
	ds_read_b128 v[220:223], v143 offset:20480
	ds_read_b128 v[228:231], v143 offset:21504
	ds_read_b128 v[232:235], v143 offset:22528
	ds_read_b128 v[236:239], v143 offset:23552
	global_load_lds_dwordx4 v[138:139], off
	s_add_i32 m0, s0, 0x2000
	s_add_u32 s0, s18, 0x160000
	v_lshl_add_u64 v[150:151], s[18:19], 0, v[128:129]
	s_addc_u32 s1, s19, 0
	s_add_i32 s50, s51, s28
	global_load_lds_dwordx4 v[150:151], off
	v_lshl_add_u64 v[164:165], s[0:1], 0, v[144:145]
	s_mov_b32 m0, s50
	v_lshl_add_u64 v[240:241], s[20:21], 0, v[128:129]
	global_load_lds_dwordx4 v[164:165], off
	v_lshl_add_u64 v[164:165], s[0:1], 0, v[128:129]
	s_add_i32 m0, s50, 0x2000
	s_nop 0
	global_load_lds_dwordx4 v[164:165], off
	v_lshl_add_u64 v[164:165], s[20:21], 0, v[144:145]
	s_mov_b32 m0, s29
	s_nop 0
	global_load_lds_dwordx4 v[164:165], off
	s_mov_b32 m0, s30
	s_nop 0
	global_load_lds_dwordx4 v[240:241], off
	s_waitcnt vmcnt(8)
	s_waitcnt lgkmcnt(0)
	s_barrier
; #define PG8_STAGE(bufoff, gbase, voff) do { _Pragma("unroll") for (int _i = 0; _i < 2; ++_i) \
;         __builtin_amdgcn_global_load_lds((const unsigned*)((const char*)(gbase) + (voff)[_i]), (LAS unsigned*)(lds + (bufoff) + ldsw + _i * 8192), 16, 0, 0); } while (0)
; #define PG8_LDA(dst, b, h) do { _Pragma("unroll") for (int m = 0; m < 4; ++m) _Pragma("unroll") for (int k = 0; k < 2; ++k) dst[m][k] = *(const LAS bf16x8*)(lds + PG8_SA(b, h) + aoff + m * 2048 + k * 1024); } while (0)
; #define PG8_LDB(dst, b, h) do { _Pragma("unroll") for (int n = 0; n < 2; ++n) _Pragma("unroll") for (int k = 0; k < 2; ++k) dst[n][k] = *(const LAS bf16x8*)(lds + PG8_SB(b, h) + boff + n * 2048 + k * 1024); } while (0)
; #define PG8_MMA(ai, bj, At, Bt) do { __builtin_amdgcn_s_setprio(1); _Pragma("unroll") for (int m = 0; m < 4; ++m) _Pragma("unroll") for (int n = 0; n < 2; ++n) _Pragma("unroll") for (int k = 0; k < 2; ++k) \
;         acc[ai][bj][m][n] = __builtin_amdgcn_mfma_f32_16x16x32_bf16(Bt[n][k], At[m][k], acc[ai][bj][m][n], 0, 0, 0); __builtin_amdgcn_s_setprio(0); } while (0)
; #define PG8_WAIT_V(n) asm volatile("s_waitcnt vmcnt(" #n ")" ::: "memory")
; #define PG8_WAIT_L(n) asm volatile("s_waitcnt lgkmcnt(" #n ")" ::: "memory")
; #define PG8_BAR __builtin_amdgcn_s_barrier()
; #define PG8_SCHED __builtin_amdgcn_sched_barrier(0)
; template <class Epi, class Sched, bool ALIGN_EPI = false, bool SP2 = false>
; __device__ __forceinline__ void gemm_phase(LAS unsigned char* lds, const Gemm g, const Sched& S, const Epi& E, const int tid) {
;     ...
;             PG8_WAIT_V(8); PG8_WAIT_L(0); PG8_BAR; PG8_MMA(1, 0, At, B0); PG8_MMA(1, 1, At, B1); PG8_BAR; PG8_SCHED;
;             PG8_LDB(B0, 1, 0); PG8_LDB(B1, 1, 1); PG8_SCHED; PG8_LDA(At, 1, 0); PG8_STAGE(PG8_SA(0, 1), a2 + hstep, voffA);
;             PG8_WAIT_V(8); PG8_WAIT_L(0); PG8_BAR; PG8_MMA(0, 0, At, B0); PG8_MMA(0, 1, At, B1); PG8_BAR; PG8_SCHED;
	s_setprio 1
	s_waitcnt lgkmcnt(0)
	v_mfma_f32_16x16x32_bf16 v[60:63], v[134:137], v[204:207], v[60:63]
	v_mfma_f32_16x16x32_bf16 v[56:59], v[156:159], v[204:207], v[56:59]
	v_mfma_f32_16x16x32_bf16 v[44:47], v[134:137], v[212:215], v[44:47]
	v_mfma_f32_16x16x32_bf16 v[40:43], v[156:159], v[212:215], v[40:43]
	v_mfma_f32_16x16x32_bf16 v[28:31], v[134:137], v[220:223], v[28:31]
	v_mfma_f32_16x16x32_bf16 v[24:27], v[156:159], v[220:223], v[24:27]
	v_mfma_f32_16x16x32_bf16 v[12:15], v[134:137], v[232:235], v[12:15]
	v_mfma_f32_16x16x32_bf16 v[8:11], v[156:159], v[232:235], v[8:11]
	v_mfma_f32_16x16x32_bf16 v[60:63], v[152:155], v[208:211], v[60:63]
	v_mfma_f32_16x16x32_bf16 v[56:59], v[160:163], v[208:211], v[56:59]
	v_mfma_f32_16x16x32_bf16 v[44:47], v[152:155], v[216:219], v[44:47]
	v_mfma_f32_16x16x32_bf16 v[40:43], v[160:163], v[216:219], v[40:43]
	v_mfma_f32_16x16x32_bf16 v[28:31], v[152:155], v[228:231], v[28:31]
	v_mfma_f32_16x16x32_bf16 v[24:27], v[160:163], v[228:231], v[24:27]
	v_mfma_f32_16x16x32_bf16 v[12:15], v[152:155], v[236:239], v[12:15]
	v_mfma_f32_16x16x32_bf16 v[8:11], v[160:163], v[236:239], v[8:11]
	s_setprio 0
	s_setprio 1
	v_mfma_f32_16x16x32_bf16 v[52:55], v[188:191], v[204:207], v[52:55]
	v_mfma_f32_16x16x32_bf16 v[48:51], v[196:199], v[204:207], v[48:51]
	v_mfma_f32_16x16x32_bf16 v[36:39], v[188:191], v[212:215], v[36:39]
	v_mfma_f32_16x16x32_bf16 v[32:35], v[196:199], v[212:215], v[32:35]
	v_mfma_f32_16x16x32_bf16 v[20:23], v[188:191], v[220:223], v[20:23]
	v_mfma_f32_16x16x32_bf16 v[16:19], v[196:199], v[220:223], v[16:19]
	v_mfma_f32_16x16x32_bf16 v[4:7], v[188:191], v[232:235], v[4:7]
	v_mfma_f32_16x16x32_bf16 v[0:3], v[196:199], v[232:235], v[0:3]
	v_mfma_f32_16x16x32_bf16 v[52:55], v[192:195], v[208:211], v[52:55]
	v_mfma_f32_16x16x32_bf16 v[48:51], v[200:203], v[208:211], v[48:51]
	v_mfma_f32_16x16x32_bf16 v[36:39], v[192:195], v[216:219], v[36:39]
	v_mfma_f32_16x16x32_bf16 v[32:35], v[200:203], v[216:219], v[32:35]
	v_mfma_f32_16x16x32_bf16 v[20:23], v[192:195], v[228:231], v[20:23]
	v_mfma_f32_16x16x32_bf16 v[16:19], v[200:203], v[228:231], v[16:19]
	v_mfma_f32_16x16x32_bf16 v[4:7], v[192:195], v[236:239], v[4:7]
	v_mfma_f32_16x16x32_bf16 v[0:3], v[200:203], v[236:239], v[0:3]
	s_setprio 0
	s_barrier
	s_add_i32 s50, 0, 0x18000
	s_add_i32 s51, 0, 0x1c000
	v_add_u32_e32 v160, s50, v141
	v_add_u32_e32 v200, s51, v141
	ds_read_b128 v[134:137], v160
	ds_read_b128 v[152:155], v160 offset:1024
	ds_read_b128 v[156:159], v160 offset:2048
	ds_read_b128 v[160:163], v160 offset:3072
	ds_read_b128 v[188:191], v200
	ds_read_b128 v[192:195], v200 offset:1024
	ds_read_b128 v[196:199], v200 offset:2048
	ds_read_b128 v[200:203], v200 offset:3072
	s_add_u32 s0, s20, 0x160000
	s_addc_u32 s1, s21, 0
	s_mov_b32 m0, s31
	v_lshl_add_u64 v[242:243], s[0:1], 0, v[144:145]
	ds_read_b128 v[204:207], v143 offset:32768
	ds_read_b128 v[208:211], v143 offset:33792
	ds_read_b128 v[212:215], v143 offset:34816
	ds_read_b128 v[216:219], v143 offset:35840
	ds_read_b128 v[220:223], v143 offset:36864
	ds_read_b128 v[228:231], v143 offset:37888
	ds_read_b128 v[232:235], v143 offset:38912
	ds_read_b128 v[236:239], v143 offset:39936
	global_load_lds_dwordx4 v[242:243], off
	v_lshl_add_u64 v[242:243], s[0:1], 0, v[128:129]
	s_mov_b32 m0, s34
	s_nop 0
	global_load_lds_dwordx4 v[242:243], off
	s_waitcnt vmcnt(8)
	s_waitcnt lgkmcnt(0)
	s_barrier
	s_setprio 1
	s_waitcnt lgkmcnt(0)
	v_mfma_f32_16x16x32_bf16 v[124:127], v[134:137], v[204:207], v[124:127]
	v_mfma_f32_16x16x32_bf16 v[120:123], v[156:159], v[204:207], v[120:123]
	v_mfma_f32_16x16x32_bf16 v[108:111], v[134:137], v[212:215], v[108:111]
	v_mfma_f32_16x16x32_bf16 v[104:107], v[156:159], v[212:215], v[104:107]
	v_mfma_f32_16x16x32_bf16 v[92:95], v[134:137], v[220:223], v[92:95]
	v_mfma_f32_16x16x32_bf16 v[88:91], v[156:159], v[220:223], v[88:91]
	v_mfma_f32_16x16x32_bf16 v[76:79], v[134:137], v[232:235], v[76:79]
	v_mfma_f32_16x16x32_bf16 v[72:75], v[156:159], v[232:235], v[72:75]
	v_mfma_f32_16x16x32_bf16 v[124:127], v[152:155], v[208:211], v[124:127]
	v_mfma_f32_16x16x32_bf16 v[120:123], v[160:163], v[208:211], v[120:123]
	v_mfma_f32_16x16x32_bf16 v[108:111], v[152:155], v[216:219], v[108:111]
	v_mfma_f32_16x16x32_bf16 v[104:107], v[160:163], v[216:219], v[104:107]
	v_mfma_f32_16x16x32_bf16 v[92:95], v[152:155], v[228:231], v[92:95]
	v_mfma_f32_16x16x32_bf16 v[88:91], v[160:163], v[228:231], v[88:91]
	v_mfma_f32_16x16x32_bf16 v[76:79], v[152:155], v[236:239], v[76:79]
	v_mfma_f32_16x16x32_bf16 v[72:75], v[160:163], v[236:239], v[72:75]
	s_setprio 0
	s_setprio 1
	v_mfma_f32_16x16x32_bf16 v[116:119], v[188:191], v[204:207], v[116:119]
	v_mfma_f32_16x16x32_bf16 v[112:115], v[196:199], v[204:207], v[112:115]
	v_mfma_f32_16x16x32_bf16 v[100:103], v[188:191], v[212:215], v[100:103]
	v_mfma_f32_16x16x32_bf16 v[96:99], v[196:199], v[212:215], v[96:99]
	v_mfma_f32_16x16x32_bf16 v[84:87], v[188:191], v[220:223], v[84:87]
	v_mfma_f32_16x16x32_bf16 v[80:83], v[196:199], v[220:223], v[80:83]
	v_mfma_f32_16x16x32_bf16 v[68:71], v[188:191], v[232:235], v[68:71]
	v_mfma_f32_16x16x32_bf16 v[64:67], v[196:199], v[232:235], v[64:67]
	v_mfma_f32_16x16x32_bf16 v[116:119], v[192:195], v[208:211], v[116:119]
	v_mfma_f32_16x16x32_bf16 v[112:115], v[200:203], v[208:211], v[112:115]
	v_mfma_f32_16x16x32_bf16 v[100:103], v[192:195], v[216:219], v[100:103]
	v_mfma_f32_16x16x32_bf16 v[96:99], v[200:203], v[216:219], v[96:99]
	v_mfma_f32_16x16x32_bf16 v[84:87], v[192:195], v[228:231], v[84:87]
	v_mfma_f32_16x16x32_bf16 v[80:83], v[200:203], v[228:231], v[80:83]
	v_mfma_f32_16x16x32_bf16 v[68:71], v[192:195], v[236:239], v[68:71]
	v_mfma_f32_16x16x32_bf16 v[64:67], v[200:203], v[236:239], v[64:67]
	s_setprio 0
	s_barrier
; #define PG8_STAGE(bufoff, gbase, voff) do { _Pragma("unroll") for (int _i = 0; _i < 2; ++_i) \
;         __builtin_amdgcn_global_load_lds((const unsigned*)((const char*)(gbase) + (voff)[_i]), (LAS unsigned*)(lds + (bufoff) + ldsw + _i * 8192), 16, 0, 0); } while (0)
; #define PG8_LDA(dst, b, h) do { _Pragma("unroll") for (int m = 0; m < 4; ++m) _Pragma("unroll") for (int k = 0; k < 2; ++k) dst[m][k] = *(const LAS bf16x8*)(lds + PG8_SA(b, h) + aoff + m * 2048 + k * 1024); } while (0)
; #define PG8_MMA(ai, bj, At, Bt) do { __builtin_amdgcn_s_setprio(1); _Pragma("unroll") for (int m = 0; m < 4; ++m) _Pragma("unroll") for (int n = 0; n < 2; ++n) _Pragma("unroll") for (int k = 0; k < 2; ++k) \
;         acc[ai][bj][m][n] = __builtin_amdgcn_mfma_f32_16x16x32_bf16(Bt[n][k], At[m][k], acc[ai][bj][m][n], 0, 0, 0); __builtin_amdgcn_s_setprio(0); } while (0)
; #define PG8_WAIT_V(n) asm volatile("s_waitcnt vmcnt(" #n ")" ::: "memory")
; #define PG8_WAIT_L(n) asm volatile("s_waitcnt lgkmcnt(" #n ")" ::: "memory")
; #define PG8_BAR __builtin_amdgcn_s_barrier()
; #define PG8_SCHED __builtin_amdgcn_sched_barrier(0)
; template <class Epi, class Sched, bool ALIGN_EPI = false, bool SP2 = false>
; __device__ __forceinline__ void gemm_phase(LAS unsigned char* lds, const Gemm g, const Sched& S, const Epi& E, const int tid) {
;     ...
;         for (int t = 0; t < nt; t += 2) {
;             const bool last = (t == nt - 2);
;             const char* a1 = cA + (size_t)(t + 1) * kstep;
;             const char* a2 = last ? nA : cA + (size_t)(t + 2) * kstep; const char* b2 = last ? nB : cB + (size_t)(t + 2) * kstep;
;             const char* a3 = a2 + kstep; const char* b3 = b2 + kstep;
;     ...
;             PG8_LDA(At, 1, 1); PG8_STAGE(PG8_SB(1, 0), b3, voffB); PG8_STAGE(PG8_SB(1, 1), b3 + hstep, voffB); PG8_STAGE(PG8_SA(1, 0), a3, voffA);
;             PG8_WAIT_V(8); PG8_WAIT_L(0); PG8_BAR; PG8_MMA(1, 0, At, B0); PG8_MMA(1, 1, At, B1); PG8_BAR; PG8_SCHED;
	s_add_i32 s0, s50, s28
	v_lshl_add_u64 v[138:139], v[138:139], 0, s[70:71]
	s_mov_b32 m0, s0
	ds_read_b128 v[204:207], v143 offset:49152
	ds_read_b128 v[208:211], v143 offset:50176
	ds_read_b128 v[212:215], v143 offset:51200
	ds_read_b128 v[216:219], v143 offset:52224
	ds_read_b128 v[220:223], v143 offset:53248
	ds_read_b128 v[228:231], v143 offset:54272
	ds_read_b128 v[232:235], v143 offset:55296
	ds_read_b128 v[236:239], v143 offset:56320
	global_load_lds_dwordx4 v[138:139], off
	s_add_i32 m0, s0, 0x2000
	s_add_u32 s0, s18, 0x160080
	v_lshl_add_u64 v[138:139], v[150:151], 0, s[70:71]
	s_addc_u32 s1, s19, 0
	s_add_i32 s18, s51, s28
	global_load_lds_dwordx4 v[138:139], off
	v_lshl_add_u64 v[138:139], s[0:1], 0, v[144:145]
	s_mov_b32 m0, s18
	s_nop 0
	global_load_lds_dwordx4 v[138:139], off
	v_lshl_add_u64 v[138:139], s[0:1], 0, v[128:129]
	s_add_i32 m0, s18, 0x2000
	s_nop 0
	global_load_lds_dwordx4 v[138:139], off
	v_lshl_add_u64 v[138:139], v[164:165], 0, s[70:71]
	s_mov_b32 m0, s38
	s_nop 0
	global_load_lds_dwordx4 v[138:139], off
	v_lshl_add_u64 v[138:139], v[240:241], 0, s[70:71]
	s_mov_b32 m0, s39
	s_nop 0
	global_load_lds_dwordx4 v[138:139], off
	s_waitcnt vmcnt(8)
	s_waitcnt lgkmcnt(0)
	s_barrier
	s_setprio 1
	s_waitcnt lgkmcnt(0)
	v_mfma_f32_16x16x32_bf16 v[60:63], v[134:137], v[204:207], v[60:63]
	v_mfma_f32_16x16x32_bf16 v[56:59], v[156:159], v[204:207], v[56:59]
	v_mfma_f32_16x16x32_bf16 v[44:47], v[134:137], v[212:215], v[44:47]
	v_mfma_f32_16x16x32_bf16 v[40:43], v[156:159], v[212:215], v[40:43]
	v_mfma_f32_16x16x32_bf16 v[28:31], v[134:137], v[220:223], v[28:31]
	v_mfma_f32_16x16x32_bf16 v[24:27], v[156:159], v[220:223], v[24:27]
	v_mfma_f32_16x16x32_bf16 v[12:15], v[134:137], v[232:235], v[12:15]
	v_mfma_f32_16x16x32_bf16 v[8:11], v[156:159], v[232:235], v[8:11]
	v_mfma_f32_16x16x32_bf16 v[60:63], v[152:155], v[208:211], v[60:63]
	v_mfma_f32_16x16x32_bf16 v[56:59], v[160:163], v[208:211], v[56:59]
	v_mfma_f32_16x16x32_bf16 v[44:47], v[152:155], v[216:219], v[44:47]
	v_mfma_f32_16x16x32_bf16 v[40:43], v[160:163], v[216:219], v[40:43]
	v_mfma_f32_16x16x32_bf16 v[28:31], v[152:155], v[228:231], v[28:31]
	v_mfma_f32_16x16x32_bf16 v[24:27], v[160:163], v[228:231], v[24:27]
	v_mfma_f32_16x16x32_bf16 v[12:15], v[152:155], v[236:239], v[12:15]
	v_mfma_f32_16x16x32_bf16 v[8:11], v[160:163], v[236:239], v[8:11]
	s_setprio 0
	s_setprio 1
	v_mfma_f32_16x16x32_bf16 v[52:55], v[188:191], v[204:207], v[52:55]
	v_mfma_f32_16x16x32_bf16 v[48:51], v[196:199], v[204:207], v[48:51]
	v_mfma_f32_16x16x32_bf16 v[36:39], v[188:191], v[212:215], v[36:39]
	v_mfma_f32_16x16x32_bf16 v[32:35], v[196:199], v[212:215], v[32:35]
	v_mfma_f32_16x16x32_bf16 v[20:23], v[188:191], v[220:223], v[20:23]
	v_mfma_f32_16x16x32_bf16 v[16:19], v[196:199], v[220:223], v[16:19]
	v_mfma_f32_16x16x32_bf16 v[4:7], v[188:191], v[232:235], v[4:7]
	v_mfma_f32_16x16x32_bf16 v[0:3], v[196:199], v[232:235], v[0:3]
	v_mfma_f32_16x16x32_bf16 v[52:55], v[192:195], v[208:211], v[52:55]
	v_mfma_f32_16x16x32_bf16 v[48:51], v[200:203], v[208:211], v[48:51]
	v_mfma_f32_16x16x32_bf16 v[36:39], v[192:195], v[216:219], v[36:39]
	v_mfma_f32_16x16x32_bf16 v[32:35], v[200:203], v[216:219], v[32:35]
	v_mfma_f32_16x16x32_bf16 v[20:23], v[192:195], v[228:231], v[20:23]
	v_mfma_f32_16x16x32_bf16 v[16:19], v[200:203], v[228:231], v[16:19]
	v_mfma_f32_16x16x32_bf16 v[4:7], v[192:195], v[236:239], v[4:7]
	v_mfma_f32_16x16x32_bf16 v[0:3], v[200:203], v[236:239], v[0:3]
	s_setprio 0
	s_add_i32 s49, s49, 2
	s_add_u32 s47, s47, 0x100
	s_addc_u32 s48, s48, 0
	s_cmpk_gt_u32 s49, 0x55
	s_mov_b64 s[0:1], s[16:17]
	s_barrier
	s_cbranch_scc0 .LBB0_1487
	s_and_b64 vcc, exec, s[12:13]
	s_cbranch_vccz .LBB0_1490
	s_barrier
